# K-loops: rendezvous barrier moved after the first 4 MFMAs of each compute segment (plus earlier latency fixes)
# speedup vs baseline: 1.0044x; 1.0027x over previous
; #define PG8_STAGE(bufoff, gbase, voff) do { _Pragma("unroll") for (int _i = 0; _i < 2; ++_i) \
;         __builtin_amdgcn_global_load_lds((const unsigned*)((const char*)(gbase) + (voff)[_i]), (LAS unsigned*)(lds + (bufoff) + ldsw + _i * 8192), 16, 0, 0); } while (0)
; #define PG8_LDA(dst, b, h) do { _Pragma("unroll") for (int m = 0; m < 4; ++m) _Pragma("unroll") for (int k = 0; k < 2; ++k) dst[m][k] = *(const LAS bf16x8*)(lds + PG8_SA(b, h) + aoff + m * 2048 + k * 1024); } while (0)
; #define PG8_LDB(dst, b, h) do { _Pragma("unroll") for (int n = 0; n < 2; ++n) _Pragma("unroll") for (int k = 0; k < 2; ++k) dst[n][k] = *(const LAS bf16x8*)(lds + PG8_SB(b, h) + boff + n * 2048 + k * 1024); } while (0)
; #define PG8_MMA(ai, bj, At, Bt) do { __builtin_amdgcn_s_setprio(1); _Pragma("unroll") for (int m = 0; m < 4; ++m) _Pragma("unroll") for (int n = 0; n < 2; ++n) _Pragma("unroll") for (int k = 0; k < 2; ++k) \
;         acc[ai][bj][m][n] = __builtin_amdgcn_mfma_f32_16x16x32_bf16(Bt[n][k], At[m][k], acc[ai][bj][m][n], 0, 0, 0); __builtin_amdgcn_s_setprio(0); } while (0)
; #define PG8_WAIT_V(n) asm volatile("s_waitcnt vmcnt(" #n ")" ::: "memory")
; #define PG8_WAIT_L(n) asm volatile("s_waitcnt lgkmcnt(" #n ")" ::: "memory")
; template <class Epi, bool ALIGN_EPI, bool SP2, bool ROWHALF = false>
; DI void gemm_phase(LAS unsigned char* lds, const Gemm g, const StaticOrder& S, const Epi& E) {
;     ...
;         for (int t = 0; t < nt; t += 2) {
;             const bool last = (t == nt - 2);
;             const char* a1 = cA + (size_t)(t + 1) * kstep;
;             const char* a2 = last ? nA : cA + (size_t)(t + 2) * kstep; const char* b2 = last ? nB : cB + (size_t)(t + 2) * kstep;
;             const char* a3 = a2 + kstep; const char* b3 = b2 + kstep;
;             if constexpr (SP2) {
;             PG8_LDB(B0, 0, 0); PG8_LDB(B1, 0, 1); PG8_SCHED; PG8_LDA(At, 0, 0); PG8_STAGE(PG8_SA(1, 1), a1 + hA1, voffA);
;             PG8_WAIT_V(8); PG8_WAIT_L(0); PG8_BAR; PG8_MMA(0, 0, At, B0); PG8_MMA(0, 1, At, B1); PG8_BAR; PG8_SCHED;
;             if constexpr (!ROWHALF) { PG8_LDA(At, 0, 1); } PG8_STAGE(PG8_SB(0, 0), b2, voffB); PG8_STAGE(PG8_SB(0, 1), b2 + hstepB, voffB); PG8_STAGE(PG8_SA(0, 0), a2 + hA0, voffA);
;             PG8_WAIT_V(8); PG8_WAIT_L(0); PG8_BAR; if constexpr (!ROWHALF) { PG8_MMA(1, 0, At, B0); PG8_MMA(1, 1, At, B1); } PG8_BAR; PG8_SCHED;
.LBB0_122:
	s_add_i32 s81, s78, 2
	s_add_u32 s36, s76, 0x80
	s_addc_u32 s37, s77, 0
	s_add_i32 s82, 0, 0x10000
	s_cmp_eq_u32 s13, s78
	s_cselect_b32 s79, s1, s37
	s_cselect_b32 s78, s0, s36
	v_add_u32_e32 v144, s82, v147
	s_cselect_b32 s37, s75, s21
	s_cselect_b32 s36, s74, s20
	s_add_i32 s83, 0, 0x14000
	ds_read_b128 v[130:133], v144
	ds_read_b128 v[150:153], v144 offset:1024
	ds_read_b128 v[154:157], v144 offset:2048
	ds_read_b128 v[158:161], v144 offset:3072
	v_add_u32_e32 v144, s83, v147
	ds_read_b128 v[164:167], v144
	ds_read_b128 v[168:171], v144 offset:1024
	ds_read_b128 v[172:175], v144 offset:2048
	ds_read_b128 v[176:179], v144 offset:3072
	v_lshl_add_u64 v[144:145], s[76:77], 0, v[140:141]
	s_add_i32 m0, s7, 0xc000
	ds_read_b128 v[180:183], v149
	ds_read_b128 v[184:187], v149 offset:1024
	ds_read_b128 v[216:219], v149 offset:2048
	ds_read_b128 v[220:223], v149 offset:3072
	ds_read_b128 v[224:227], v149 offset:4096
	ds_read_b128 v[228:231], v149 offset:5120
	ds_read_b128 v[232:235], v149 offset:6144
	ds_read_b128 v[236:239], v149 offset:7168
	global_load_lds_dwordx4 v[144:145], off
	v_lshl_add_u64 v[144:145], s[76:77], 0, v[142:143]
	s_add_i32 m0, s7, 0xe000
	s_nop 0
	global_load_lds_dwordx4 v[144:145], off
	s_waitcnt vmcnt(8)
	s_waitcnt lgkmcnt(0)
	s_setprio 1
	v_mfma_f32_16x16x32_bf16 v[118:121], v[130:133], v[180:183], v[118:121]
	v_mfma_f32_16x16x32_bf16 v[126:129], v[154:157], v[180:183], v[126:129]
	v_mfma_f32_16x16x32_bf16 v[110:113], v[130:133], v[216:219], v[110:113]
	v_mfma_f32_16x16x32_bf16 v[106:109], v[154:157], v[216:219], v[106:109]
	s_barrier
	v_mfma_f32_16x16x32_bf16 v[92:95], v[130:133], v[224:227], v[92:95]
	v_mfma_f32_16x16x32_bf16 v[88:91], v[154:157], v[224:227], v[88:91]
	v_mfma_f32_16x16x32_bf16 v[76:79], v[130:133], v[232:235], v[76:79]
	v_mfma_f32_16x16x32_bf16 v[72:75], v[154:157], v[232:235], v[72:75]
	v_mfma_f32_16x16x32_bf16 v[118:121], v[150:153], v[184:187], v[118:121]
	v_mfma_f32_16x16x32_bf16 v[126:129], v[158:161], v[184:187], v[126:129]
	v_mfma_f32_16x16x32_bf16 v[110:113], v[150:153], v[220:223], v[110:113]
	v_mfma_f32_16x16x32_bf16 v[106:109], v[158:161], v[220:223], v[106:109]
	v_mfma_f32_16x16x32_bf16 v[92:95], v[150:153], v[228:231], v[92:95]
	v_mfma_f32_16x16x32_bf16 v[88:91], v[158:161], v[228:231], v[88:91]
	v_mfma_f32_16x16x32_bf16 v[76:79], v[150:153], v[236:239], v[76:79]
	v_mfma_f32_16x16x32_bf16 v[72:75], v[158:161], v[236:239], v[72:75]
	s_setprio 0
	s_setprio 1
	v_mfma_f32_16x16x32_bf16 v[122:125], v[164:167], v[180:183], v[122:125]
	v_mfma_f32_16x16x32_bf16 v[114:117], v[172:175], v[180:183], v[114:117]
	v_mfma_f32_16x16x32_bf16 v[102:105], v[164:167], v[216:219], v[102:105]
	v_mfma_f32_16x16x32_bf16 v[98:101], v[172:175], v[216:219], v[98:101]
	v_mfma_f32_16x16x32_bf16 v[84:87], v[164:167], v[224:227], v[84:87]
	v_mfma_f32_16x16x32_bf16 v[80:83], v[172:175], v[224:227], v[80:83]
	v_mfma_f32_16x16x32_bf16 v[68:71], v[164:167], v[232:235], v[68:71]
	v_mfma_f32_16x16x32_bf16 v[64:67], v[172:175], v[232:235], v[64:67]
	v_mfma_f32_16x16x32_bf16 v[122:125], v[168:171], v[184:187], v[122:125]
	v_mfma_f32_16x16x32_bf16 v[114:117], v[176:179], v[184:187], v[114:117]
	v_mfma_f32_16x16x32_bf16 v[102:105], v[168:171], v[220:223], v[102:105]
	v_mfma_f32_16x16x32_bf16 v[98:101], v[176:179], v[220:223], v[98:101]
	v_mfma_f32_16x16x32_bf16 v[84:87], v[168:171], v[228:231], v[84:87]
	v_mfma_f32_16x16x32_bf16 v[80:83], v[176:179], v[228:231], v[80:83]
	v_mfma_f32_16x16x32_bf16 v[68:71], v[168:171], v[236:239], v[68:71]
	v_mfma_f32_16x16x32_bf16 v[64:67], v[176:179], v[236:239], v[64:67]
	s_setprio 0
	s_barrier
	s_add_i32 s82, s82, s4
	v_lshl_add_u64 v[144:145], s[36:37], 0, v[96:97]
	s_mov_b32 m0, s82
	ds_read_b128 v[180:183], v149 offset:16384
	ds_read_b128 v[184:187], v149 offset:17408
	ds_read_b128 v[216:219], v149 offset:18432
	ds_read_b128 v[220:223], v149 offset:19456
	ds_read_b128 v[224:227], v149 offset:20480
	ds_read_b128 v[228:231], v149 offset:21504
	ds_read_b128 v[232:235], v149 offset:22528
	ds_read_b128 v[236:239], v149 offset:23552
	global_load_lds_dwordx4 v[144:145], off
	s_add_i32 m0, s82, 0x2000
	v_lshl_add_u64 v[192:193], s[36:37], 0, v[134:135]
	s_add_u32 s36, s36, s28
	s_addc_u32 s37, s37, 0
	s_add_i32 s82, s83, s4
	global_load_lds_dwordx4 v[192:193], off
	v_lshl_add_u64 v[194:195], s[36:37], 0, v[96:97]
	s_mov_b32 m0, s82
	v_lshl_add_u64 v[240:241], s[36:37], 0, v[134:135]
	global_load_lds_dwordx4 v[194:195], off
	s_add_i32 m0, s82, 0x2000
	v_lshl_add_u64 v[242:243], s[78:79], 0, v[138:139]
	global_load_lds_dwordx4 v[240:241], off
	s_mov_b32 m0, s7
	v_lshl_add_u64 v[244:245], s[78:79], 0, v[136:137]
	global_load_lds_dwordx4 v[242:243], off
	s_mov_b32 m0, s8
	s_nop 0
	global_load_lds_dwordx4 v[244:245], off
	s_waitcnt vmcnt(8)
	s_waitcnt lgkmcnt(0)
	s_setprio 1
	v_mfma_f32_16x16x32_bf16 v[60:63], v[130:133], v[180:183], v[60:63]
	v_mfma_f32_16x16x32_bf16 v[56:59], v[154:157], v[180:183], v[56:59]
	v_mfma_f32_16x16x32_bf16 v[44:47], v[130:133], v[216:219], v[44:47]
	v_mfma_f32_16x16x32_bf16 v[40:43], v[154:157], v[216:219], v[40:43]
	s_barrier
; #define PG8_STAGE(bufoff, gbase, voff) do { _Pragma("unroll") for (int _i = 0; _i < 2; ++_i) \
;         __builtin_amdgcn_global_load_lds((const unsigned*)((const char*)(gbase) + (voff)[_i]), (LAS unsigned*)(lds + (bufoff) + ldsw + _i * 8192), 16, 0, 0); } while (0)
; #define PG8_LDA(dst, b, h) do { _Pragma("unroll") for (int m = 0; m < 4; ++m) _Pragma("unroll") for (int k = 0; k < 2; ++k) dst[m][k] = *(const LAS bf16x8*)(lds + PG8_SA(b, h) + aoff + m * 2048 + k * 1024); } while (0)
; #define PG8_LDB(dst, b, h) do { _Pragma("unroll") for (int n = 0; n < 2; ++n) _Pragma("unroll") for (int k = 0; k < 2; ++k) dst[n][k] = *(const LAS bf16x8*)(lds + PG8_SB(b, h) + boff + n * 2048 + k * 1024); } while (0)
; #define PG8_MMA(ai, bj, At, Bt) do { __builtin_amdgcn_s_setprio(1); _Pragma("unroll") for (int m = 0; m < 4; ++m) _Pragma("unroll") for (int n = 0; n < 2; ++n) _Pragma("unroll") for (int k = 0; k < 2; ++k) \
;         acc[ai][bj][m][n] = __builtin_amdgcn_mfma_f32_16x16x32_bf16(Bt[n][k], At[m][k], acc[ai][bj][m][n], 0, 0, 0); __builtin_amdgcn_s_setprio(0); } while (0)
; #define PG8_WAIT_V(n) asm volatile("s_waitcnt vmcnt(" #n ")" ::: "memory")
; #define PG8_WAIT_L(n) asm volatile("s_waitcnt lgkmcnt(" #n ")" ::: "memory")
; #define PG8_BAR __builtin_amdgcn_s_barrier()
; #define PG8_SCHED __builtin_amdgcn_sched_barrier(0)
; template <class Epi, bool ALIGN_EPI, bool SP2, bool ROWHALF = false>
; DI void gemm_phase(LAS unsigned char* lds, const Gemm g, const StaticOrder& S, const Epi& E) {
;     ...
;             PG8_WAIT_V(8); PG8_WAIT_L(0); PG8_BAR; if constexpr (!ROWHALF) { PG8_MMA(1, 0, At, B0); PG8_MMA(1, 1, At, B1); } PG8_BAR; PG8_SCHED;
;             PG8_LDB(B0, 1, 0); PG8_LDB(B1, 1, 1); PG8_SCHED; PG8_LDA(At, 1, 0); PG8_STAGE(PG8_SA(0, 1), a2 + hA1, voffA);
;             PG8_WAIT_V(8); PG8_WAIT_L(0); PG8_BAR; PG8_MMA(0, 0, At, B0); PG8_MMA(0, 1, At, B1); PG8_BAR; PG8_SCHED;
	v_mfma_f32_16x16x32_bf16 v[28:31], v[130:133], v[224:227], v[28:31]
	v_mfma_f32_16x16x32_bf16 v[24:27], v[154:157], v[224:227], v[24:27]
	v_mfma_f32_16x16x32_bf16 v[12:15], v[130:133], v[232:235], v[12:15]
	v_mfma_f32_16x16x32_bf16 v[8:11], v[154:157], v[232:235], v[8:11]
	v_mfma_f32_16x16x32_bf16 v[60:63], v[150:153], v[184:187], v[60:63]
	v_mfma_f32_16x16x32_bf16 v[56:59], v[158:161], v[184:187], v[56:59]
	v_mfma_f32_16x16x32_bf16 v[44:47], v[150:153], v[220:223], v[44:47]
	v_mfma_f32_16x16x32_bf16 v[40:43], v[158:161], v[220:223], v[40:43]
	v_mfma_f32_16x16x32_bf16 v[28:31], v[150:153], v[228:231], v[28:31]
	v_mfma_f32_16x16x32_bf16 v[24:27], v[158:161], v[228:231], v[24:27]
	v_mfma_f32_16x16x32_bf16 v[12:15], v[150:153], v[236:239], v[12:15]
	v_mfma_f32_16x16x32_bf16 v[8:11], v[158:161], v[236:239], v[8:11]
	s_setprio 0
	s_setprio 1
	v_mfma_f32_16x16x32_bf16 v[52:55], v[164:167], v[180:183], v[52:55]
	v_mfma_f32_16x16x32_bf16 v[48:51], v[172:175], v[180:183], v[48:51]
	v_mfma_f32_16x16x32_bf16 v[36:39], v[164:167], v[216:219], v[36:39]
	v_mfma_f32_16x16x32_bf16 v[32:35], v[172:175], v[216:219], v[32:35]
	v_mfma_f32_16x16x32_bf16 v[20:23], v[164:167], v[224:227], v[20:23]
	v_mfma_f32_16x16x32_bf16 v[16:19], v[172:175], v[224:227], v[16:19]
	v_mfma_f32_16x16x32_bf16 v[4:7], v[164:167], v[232:235], v[4:7]
	v_mfma_f32_16x16x32_bf16 v[0:3], v[172:175], v[232:235], v[0:3]
	v_mfma_f32_16x16x32_bf16 v[52:55], v[168:171], v[184:187], v[52:55]
	v_mfma_f32_16x16x32_bf16 v[48:51], v[176:179], v[184:187], v[48:51]
	v_mfma_f32_16x16x32_bf16 v[36:39], v[168:171], v[220:223], v[36:39]
	v_mfma_f32_16x16x32_bf16 v[32:35], v[176:179], v[220:223], v[32:35]
	v_mfma_f32_16x16x32_bf16 v[20:23], v[168:171], v[228:231], v[20:23]
	v_mfma_f32_16x16x32_bf16 v[16:19], v[176:179], v[228:231], v[16:19]
	v_mfma_f32_16x16x32_bf16 v[4:7], v[168:171], v[236:239], v[4:7]
	v_mfma_f32_16x16x32_bf16 v[0:3], v[176:179], v[236:239], v[0:3]
	s_setprio 0
	s_barrier
	s_add_i32 s82, 0, 0x18000
	s_add_i32 s83, 0, 0x1c000
	v_add_u32_e32 v158, s82, v147
	v_add_u32_e32 v176, s83, v147
	ds_read_b128 v[130:133], v158
	ds_read_b128 v[150:153], v158 offset:1024
	ds_read_b128 v[154:157], v158 offset:2048
	ds_read_b128 v[158:161], v158 offset:3072
	ds_read_b128 v[164:167], v176
	ds_read_b128 v[168:171], v176 offset:1024
	ds_read_b128 v[172:175], v176 offset:2048
	ds_read_b128 v[176:179], v176 offset:3072
	s_add_u32 s36, s78, s18
	s_addc_u32 s37, s79, 0
	s_mov_b32 m0, s9
	v_lshl_add_u64 v[246:247], s[36:37], 0, v[138:139]
	ds_read_b128 v[180:183], v149 offset:32768
	ds_read_b128 v[184:187], v149 offset:33792
	ds_read_b128 v[216:219], v149 offset:34816
	ds_read_b128 v[220:223], v149 offset:35840
	ds_read_b128 v[224:227], v149 offset:36864
	ds_read_b128 v[228:231], v149 offset:37888
	ds_read_b128 v[232:235], v149 offset:38912
	ds_read_b128 v[236:239], v149 offset:39936
	global_load_lds_dwordx4 v[246:247], off
	v_lshl_add_u64 v[246:247], s[36:37], 0, v[136:137]
	s_mov_b32 m0, s10
	s_nop 0
	global_load_lds_dwordx4 v[246:247], off
	s_waitcnt vmcnt(8)
	s_waitcnt lgkmcnt(0)
	s_setprio 1
	v_mfma_f32_16x16x32_bf16 v[118:121], v[130:133], v[180:183], v[118:121]
	v_mfma_f32_16x16x32_bf16 v[126:129], v[154:157], v[180:183], v[126:129]
	v_mfma_f32_16x16x32_bf16 v[110:113], v[130:133], v[216:219], v[110:113]
	v_mfma_f32_16x16x32_bf16 v[106:109], v[154:157], v[216:219], v[106:109]
	s_barrier
	v_mfma_f32_16x16x32_bf16 v[92:95], v[130:133], v[224:227], v[92:95]
	v_mfma_f32_16x16x32_bf16 v[88:91], v[154:157], v[224:227], v[88:91]
	v_mfma_f32_16x16x32_bf16 v[76:79], v[130:133], v[232:235], v[76:79]
	v_mfma_f32_16x16x32_bf16 v[72:75], v[154:157], v[232:235], v[72:75]
	v_mfma_f32_16x16x32_bf16 v[118:121], v[150:153], v[184:187], v[118:121]
	v_mfma_f32_16x16x32_bf16 v[126:129], v[158:161], v[184:187], v[126:129]
	v_mfma_f32_16x16x32_bf16 v[110:113], v[150:153], v[220:223], v[110:113]
	v_mfma_f32_16x16x32_bf16 v[106:109], v[158:161], v[220:223], v[106:109]
	v_mfma_f32_16x16x32_bf16 v[92:95], v[150:153], v[228:231], v[92:95]
	v_mfma_f32_16x16x32_bf16 v[88:91], v[158:161], v[228:231], v[88:91]
	v_mfma_f32_16x16x32_bf16 v[76:79], v[150:153], v[236:239], v[76:79]
	v_mfma_f32_16x16x32_bf16 v[72:75], v[158:161], v[236:239], v[72:75]
	s_setprio 0
	s_setprio 1
	v_mfma_f32_16x16x32_bf16 v[122:125], v[164:167], v[180:183], v[122:125]
	v_mfma_f32_16x16x32_bf16 v[114:117], v[172:175], v[180:183], v[114:117]
	v_mfma_f32_16x16x32_bf16 v[102:105], v[164:167], v[216:219], v[102:105]
	v_mfma_f32_16x16x32_bf16 v[98:101], v[172:175], v[216:219], v[98:101]
	v_mfma_f32_16x16x32_bf16 v[84:87], v[164:167], v[224:227], v[84:87]
	v_mfma_f32_16x16x32_bf16 v[80:83], v[172:175], v[224:227], v[80:83]
	v_mfma_f32_16x16x32_bf16 v[68:71], v[164:167], v[232:235], v[68:71]
	v_mfma_f32_16x16x32_bf16 v[64:67], v[172:175], v[232:235], v[64:67]
	v_mfma_f32_16x16x32_bf16 v[122:125], v[168:171], v[184:187], v[122:125]
	v_mfma_f32_16x16x32_bf16 v[114:117], v[176:179], v[184:187], v[114:117]
	v_mfma_f32_16x16x32_bf16 v[102:105], v[168:171], v[220:223], v[102:105]
	v_mfma_f32_16x16x32_bf16 v[98:101], v[176:179], v[220:223], v[98:101]
	v_mfma_f32_16x16x32_bf16 v[84:87], v[168:171], v[228:231], v[84:87]
	v_mfma_f32_16x16x32_bf16 v[80:83], v[176:179], v[228:231], v[80:83]
	v_mfma_f32_16x16x32_bf16 v[68:71], v[168:171], v[236:239], v[68:71]
	v_mfma_f32_16x16x32_bf16 v[64:67], v[176:179], v[236:239], v[64:67]
	s_setprio 0
	s_barrier
; #define PG8_STAGE(bufoff, gbase, voff) do { _Pragma("unroll") for (int _i = 0; _i < 2; ++_i) \
;         __builtin_amdgcn_global_load_lds((const unsigned*)((const char*)(gbase) + (voff)[_i]), (LAS unsigned*)(lds + (bufoff) + ldsw + _i * 8192), 16, 0, 0); } while (0)
; #define PG8_LDA(dst, b, h) do { _Pragma("unroll") for (int m = 0; m < 4; ++m) _Pragma("unroll") for (int k = 0; k < 2; ++k) dst[m][k] = *(const LAS bf16x8*)(lds + PG8_SA(b, h) + aoff + m * 2048 + k * 1024); } while (0)
; #define PG8_MMA(ai, bj, At, Bt) do { __builtin_amdgcn_s_setprio(1); _Pragma("unroll") for (int m = 0; m < 4; ++m) _Pragma("unroll") for (int n = 0; n < 2; ++n) _Pragma("unroll") for (int k = 0; k < 2; ++k) \
;         acc[ai][bj][m][n] = __builtin_amdgcn_mfma_f32_16x16x32_bf16(Bt[n][k], At[m][k], acc[ai][bj][m][n], 0, 0, 0); __builtin_amdgcn_s_setprio(0); } while (0)
; #define PG8_WAIT_V(n) asm volatile("s_waitcnt vmcnt(" #n ")" ::: "memory")
; #define PG8_WAIT_L(n) asm volatile("s_waitcnt lgkmcnt(" #n ")" ::: "memory")
; #define PG8_BAR __builtin_amdgcn_s_barrier()
; #define PG8_SCHED __builtin_amdgcn_sched_barrier(0)
; template <class Epi, bool ALIGN_EPI, bool SP2, bool ROWHALF = false>
; DI void gemm_phase(LAS unsigned char* lds, const Gemm g, const StaticOrder& S, const Epi& E) {
;     ...
;             if constexpr (!ROWHALF) { PG8_LDA(At, 1, 1); } PG8_STAGE(PG8_SB(1, 0), b3, voffB); PG8_STAGE(PG8_SB(1, 1), b3 + hstepB, voffB); PG8_STAGE(PG8_SA(1, 0), a3 + hA0, voffA);
;             PG8_WAIT_V(8); PG8_WAIT_L(0); PG8_BAR; if constexpr (!ROWHALF) { PG8_MMA(1, 0, At, B0); PG8_MMA(1, 1, At, B1); } PG8_BAR; PG8_SCHED;
	s_add_i32 s36, s82, s4
	v_lshl_add_u64 v[144:145], v[144:145], 0, s[38:39]
	s_mov_b32 m0, s36
	ds_read_b128 v[180:183], v149 offset:49152
	ds_read_b128 v[184:187], v149 offset:50176
	ds_read_b128 v[216:219], v149 offset:51200
	ds_read_b128 v[220:223], v149 offset:52224
	ds_read_b128 v[224:227], v149 offset:53248
	ds_read_b128 v[228:231], v149 offset:54272
	ds_read_b128 v[232:235], v149 offset:55296
	ds_read_b128 v[236:239], v149 offset:56320
	global_load_lds_dwordx4 v[144:145], off
	v_lshl_add_u64 v[144:145], v[192:193], 0, s[38:39]
	s_add_i32 m0, s36, 0x2000
	s_add_i32 s36, s83, s4
	global_load_lds_dwordx4 v[144:145], off
	v_lshl_add_u64 v[144:145], v[194:195], 0, s[38:39]
	s_mov_b32 m0, s36
	s_nop 0
	global_load_lds_dwordx4 v[144:145], off
	v_lshl_add_u64 v[144:145], v[240:241], 0, s[38:39]
	s_add_i32 m0, s36, 0x2000
	s_nop 0
	global_load_lds_dwordx4 v[144:145], off
	v_lshl_add_u64 v[144:145], v[242:243], 0, s[38:39]
	s_mov_b32 m0, s26
	s_nop 0
	global_load_lds_dwordx4 v[144:145], off
	v_lshl_add_u64 v[144:145], v[244:245], 0, s[38:39]
	s_mov_b32 m0, s27
	s_nop 0
	global_load_lds_dwordx4 v[144:145], off
	s_waitcnt vmcnt(8)
	s_waitcnt lgkmcnt(0)
	s_setprio 1
	v_mfma_f32_16x16x32_bf16 v[60:63], v[130:133], v[180:183], v[60:63]
	v_mfma_f32_16x16x32_bf16 v[56:59], v[154:157], v[180:183], v[56:59]
	v_mfma_f32_16x16x32_bf16 v[44:47], v[130:133], v[216:219], v[44:47]
	v_mfma_f32_16x16x32_bf16 v[40:43], v[154:157], v[216:219], v[40:43]
	s_barrier
	v_mfma_f32_16x16x32_bf16 v[28:31], v[130:133], v[224:227], v[28:31]
	v_mfma_f32_16x16x32_bf16 v[24:27], v[154:157], v[224:227], v[24:27]
	v_mfma_f32_16x16x32_bf16 v[12:15], v[130:133], v[232:235], v[12:15]
	v_mfma_f32_16x16x32_bf16 v[8:11], v[154:157], v[232:235], v[8:11]
	v_mfma_f32_16x16x32_bf16 v[60:63], v[150:153], v[184:187], v[60:63]
	v_mfma_f32_16x16x32_bf16 v[56:59], v[158:161], v[184:187], v[56:59]
	v_mfma_f32_16x16x32_bf16 v[44:47], v[150:153], v[220:223], v[44:47]
	v_mfma_f32_16x16x32_bf16 v[40:43], v[158:161], v[220:223], v[40:43]
	v_mfma_f32_16x16x32_bf16 v[28:31], v[150:153], v[228:231], v[28:31]
	v_mfma_f32_16x16x32_bf16 v[24:27], v[158:161], v[228:231], v[24:27]
	v_mfma_f32_16x16x32_bf16 v[12:15], v[150:153], v[236:239], v[12:15]
	v_mfma_f32_16x16x32_bf16 v[8:11], v[158:161], v[236:239], v[8:11]
	s_setprio 0
	s_setprio 1
	v_mfma_f32_16x16x32_bf16 v[52:55], v[164:167], v[180:183], v[52:55]
	v_mfma_f32_16x16x32_bf16 v[48:51], v[172:175], v[180:183], v[48:51]
	v_mfma_f32_16x16x32_bf16 v[36:39], v[164:167], v[216:219], v[36:39]
	v_mfma_f32_16x16x32_bf16 v[32:35], v[172:175], v[216:219], v[32:35]
	v_mfma_f32_16x16x32_bf16 v[20:23], v[164:167], v[224:227], v[20:23]
	v_mfma_f32_16x16x32_bf16 v[16:19], v[172:175], v[224:227], v[16:19]
	v_mfma_f32_16x16x32_bf16 v[4:7], v[164:167], v[232:235], v[4:7]
	v_mfma_f32_16x16x32_bf16 v[0:3], v[172:175], v[232:235], v[0:3]
	v_mfma_f32_16x16x32_bf16 v[52:55], v[168:171], v[184:187], v[52:55]
	v_mfma_f32_16x16x32_bf16 v[48:51], v[176:179], v[184:187], v[48:51]
	v_mfma_f32_16x16x32_bf16 v[36:39], v[168:171], v[220:223], v[36:39]
	v_mfma_f32_16x16x32_bf16 v[32:35], v[176:179], v[220:223], v[32:35]
	v_mfma_f32_16x16x32_bf16 v[20:23], v[168:171], v[228:231], v[20:23]
	v_mfma_f32_16x16x32_bf16 v[16:19], v[176:179], v[228:231], v[16:19]
	v_mfma_f32_16x16x32_bf16 v[4:7], v[168:171], v[236:239], v[4:7]
	v_mfma_f32_16x16x32_bf16 v[0:3], v[176:179], v[236:239], v[0:3]
	s_setprio 0
	s_barrier
	s_add_u32 s76, s76, 0x100
	s_addc_u32 s77, s77, 0
	s_add_u32 s20, s20, 0x100
	s_addc_u32 s21, s21, 0
	s_cmp_ge_u32 s81, s29
	s_mov_b32 s78, s81
	s_cbranch_scc0 .LBB0_122

; #define PG8_STAGE(bufoff, gbase, voff) do { _Pragma("unroll") for (int _i = 0; _i < 2; ++_i) \
;         __builtin_amdgcn_global_load_lds((const unsigned*)((const char*)(gbase) + (voff)[_i]), (LAS unsigned*)(lds + (bufoff) + ldsw + _i * 8192), 16, 0, 0); } while (0)
; #define PG8_LDA(dst, b, h) do { _Pragma("unroll") for (int m = 0; m < 4; ++m) _Pragma("unroll") for (int k = 0; k < 2; ++k) dst[m][k] = *(const LAS bf16x8*)(lds + PG8_SA(b, h) + aoff + m * 2048 + k * 1024); } while (0)
; #define PG8_LDB(dst, b, h) do { _Pragma("unroll") for (int n = 0; n < 2; ++n) _Pragma("unroll") for (int k = 0; k < 2; ++k) dst[n][k] = *(const LAS bf16x8*)(lds + PG8_SB(b, h) + boff + n * 2048 + k * 1024); } while (0)
; #define PG8_MMA(ai, bj, At, Bt) do { __builtin_amdgcn_s_setprio(1); _Pragma("unroll") for (int m = 0; m < 4; ++m) _Pragma("unroll") for (int n = 0; n < 2; ++n) _Pragma("unroll") for (int k = 0; k < 2; ++k) \
;         acc[ai][bj][m][n] = __builtin_amdgcn_mfma_f32_16x16x32_bf16(Bt[n][k], At[m][k], acc[ai][bj][m][n], 0, 0, 0); __builtin_amdgcn_s_setprio(0); } while (0)
; #define PG8_WAIT_V(n) asm volatile("s_waitcnt vmcnt(" #n ")" ::: "memory")
; #define PG8_WAIT_L(n) asm volatile("s_waitcnt lgkmcnt(" #n ")" ::: "memory")
; template <class Epi, bool ALIGN_EPI, bool SP2, bool ROWHALF = false>
; DI void gemm_phase(LAS unsigned char* lds, const Gemm g, const StaticOrder& S, const Epi& E) {
;     ...
;         for (int t = 0; t < nt; t += 2) {
;             const bool last = (t == nt - 2);
;             const char* a1 = cA + (size_t)(t + 1) * kstep;
;             const char* a2 = last ? nA : cA + (size_t)(t + 2) * kstep; const char* b2 = last ? nB : cB + (size_t)(t + 2) * kstep;
;             const char* a3 = a2 + kstep; const char* b3 = b2 + kstep;
;             if constexpr (SP2) {
;             PG8_LDB(B0, 0, 0); PG8_LDB(B1, 0, 1); PG8_SCHED; PG8_LDA(At, 0, 0); PG8_STAGE(PG8_SA(1, 1), a1 + hA1, voffA);
;             PG8_WAIT_V(8); PG8_WAIT_L(0); PG8_BAR; PG8_MMA(0, 0, At, B0); PG8_MMA(0, 1, At, B1); PG8_BAR; PG8_SCHED;
;             if constexpr (!ROWHALF) { PG8_LDA(At, 0, 1); } PG8_STAGE(PG8_SB(0, 0), b2, voffB); PG8_STAGE(PG8_SB(0, 1), b2 + hstepB, voffB); PG8_STAGE(PG8_SA(0, 0), a2 + hA0, voffA);
;             PG8_WAIT_V(8); PG8_WAIT_L(0); PG8_BAR; if constexpr (!ROWHALF) { PG8_MMA(1, 0, At, B0); PG8_MMA(1, 1, At, B1); } PG8_BAR; PG8_SCHED;
.LBB0_159:
	s_add_i32 s36, s37, 2
	s_add_u32 s78, s76, 0x80
	s_addc_u32 s79, s77, 0
	s_add_i32 s81, 0, 0x10000
	s_cmp_eq_u32 s13, s37
	s_cselect_b32 s79, s1, s79
	s_cselect_b32 s78, s0, s78
	v_add_u32_e32 v96, s81, v146
	s_cselect_b32 s83, s75, s21
	s_cselect_b32 s82, s74, s20
	s_add_i32 s37, 0, 0x14000
	ds_read_b128 v[148:151], v96
	ds_read_b128 v[152:155], v96 offset:1024
	ds_read_b128 v[156:159], v96 offset:2048
	ds_read_b128 v[164:167], v96 offset:3072
	v_add_u32_e32 v96, s37, v146
	ds_read_b128 v[168:171], v96
	ds_read_b128 v[172:175], v96 offset:1024
	ds_read_b128 v[176:179], v96 offset:2048
	ds_read_b128 v[180:183], v96 offset:3072
	v_lshl_add_u64 v[98:99], s[76:77], 0, v[140:141]
	s_add_i32 m0, s7, 0xc000
	ds_read_b128 v[184:187], v147
	ds_read_b128 v[218:221], v147 offset:1024
	ds_read_b128 v[222:225], v147 offset:2048
	ds_read_b128 v[226:229], v147 offset:3072
	ds_read_b128 v[230:233], v147 offset:4096
	ds_read_b128 v[234:237], v147 offset:5120
	ds_read_b128 v[238:241], v147 offset:6144
	ds_read_b128 v[242:245], v147 offset:7168
	global_load_lds_dwordx4 v[98:99], off
	v_lshl_add_u64 v[98:99], s[76:77], 0, v[142:143]
	s_add_i32 m0, s7, 0xe000
	s_nop 0
	global_load_lds_dwordx4 v[98:99], off
	s_waitcnt vmcnt(8)
	s_waitcnt lgkmcnt(0)
	s_setprio 1
	v_mfma_f32_16x16x32_bf16 v[4:7], v[148:151], v[184:187], v[4:7]
	v_mfma_f32_16x16x32_bf16 v[0:3], v[156:159], v[184:187], v[0:3]
	v_mfma_f32_16x16x32_bf16 v[20:23], v[148:151], v[222:225], v[20:23]
	v_mfma_f32_16x16x32_bf16 v[16:19], v[156:159], v[222:225], v[16:19]
	s_barrier
	v_mfma_f32_16x16x32_bf16 v[36:39], v[148:151], v[230:233], v[36:39]
	v_mfma_f32_16x16x32_bf16 v[32:35], v[156:159], v[230:233], v[32:35]
	v_mfma_f32_16x16x32_bf16 v[52:55], v[148:151], v[238:241], v[52:55]
	v_mfma_f32_16x16x32_bf16 v[48:51], v[156:159], v[238:241], v[48:51]
	v_mfma_f32_16x16x32_bf16 v[4:7], v[152:155], v[218:221], v[4:7]
	v_mfma_f32_16x16x32_bf16 v[0:3], v[164:167], v[218:221], v[0:3]
	v_mfma_f32_16x16x32_bf16 v[20:23], v[152:155], v[226:229], v[20:23]
	v_mfma_f32_16x16x32_bf16 v[16:19], v[164:167], v[226:229], v[16:19]
	v_mfma_f32_16x16x32_bf16 v[36:39], v[152:155], v[234:237], v[36:39]
	v_mfma_f32_16x16x32_bf16 v[32:35], v[164:167], v[234:237], v[32:35]
	v_mfma_f32_16x16x32_bf16 v[52:55], v[152:155], v[242:245], v[52:55]
	v_mfma_f32_16x16x32_bf16 v[48:51], v[164:167], v[242:245], v[48:51]
	s_setprio 0
	s_setprio 1
	v_mfma_f32_16x16x32_bf16 v[12:15], v[168:171], v[184:187], v[12:15]
	v_mfma_f32_16x16x32_bf16 v[8:11], v[176:179], v[184:187], v[8:11]
	v_mfma_f32_16x16x32_bf16 v[28:31], v[168:171], v[222:225], v[28:31]
	v_mfma_f32_16x16x32_bf16 v[24:27], v[176:179], v[222:225], v[24:27]
	v_mfma_f32_16x16x32_bf16 v[44:47], v[168:171], v[230:233], v[44:47]
	v_mfma_f32_16x16x32_bf16 v[40:43], v[176:179], v[230:233], v[40:43]
	v_mfma_f32_16x16x32_bf16 v[60:63], v[168:171], v[238:241], v[60:63]
	v_mfma_f32_16x16x32_bf16 v[56:59], v[176:179], v[238:241], v[56:59]
	v_mfma_f32_16x16x32_bf16 v[12:15], v[172:175], v[218:221], v[12:15]
	v_mfma_f32_16x16x32_bf16 v[8:11], v[180:183], v[218:221], v[8:11]
	v_mfma_f32_16x16x32_bf16 v[28:31], v[172:175], v[226:229], v[28:31]
	v_mfma_f32_16x16x32_bf16 v[24:27], v[180:183], v[226:229], v[24:27]
	v_mfma_f32_16x16x32_bf16 v[44:47], v[172:175], v[234:237], v[44:47]
	v_mfma_f32_16x16x32_bf16 v[40:43], v[180:183], v[234:237], v[40:43]
	v_mfma_f32_16x16x32_bf16 v[60:63], v[172:175], v[242:245], v[60:63]
	v_mfma_f32_16x16x32_bf16 v[56:59], v[180:183], v[242:245], v[56:59]
	s_setprio 0
	s_barrier
	s_add_i32 s81, s81, s4
	v_lshl_add_u64 v[160:161], s[82:83], 0, v[136:137]
	s_mov_b32 m0, s81
	ds_read_b128 v[184:187], v147 offset:16384
	ds_read_b128 v[218:221], v147 offset:17408
	ds_read_b128 v[222:225], v147 offset:18432
	ds_read_b128 v[226:229], v147 offset:19456
	ds_read_b128 v[230:233], v147 offset:20480
	ds_read_b128 v[234:237], v147 offset:21504
	ds_read_b128 v[238:241], v147 offset:22528
	ds_read_b128 v[242:245], v147 offset:23552
	global_load_lds_dwordx4 v[160:161], off
	s_add_i32 m0, s81, 0x2000
	v_lshl_add_u64 v[246:247], s[82:83], 0, v[108:109]
	s_add_u32 s82, s82, s28
	s_addc_u32 s83, s83, 0
	s_add_i32 s37, s37, s4
	global_load_lds_dwordx4 v[246:247], off
	v_lshl_add_u64 v[248:249], s[82:83], 0, v[136:137]
	s_mov_b32 m0, s37
	v_lshl_add_u64 v[250:251], s[82:83], 0, v[108:109]
	global_load_lds_dwordx4 v[248:249], off
	s_add_i32 m0, s37, 0x2000
	v_lshl_add_u64 v[192:193], s[78:79], 0, v[138:139]
	global_load_lds_dwordx4 v[250:251], off
	s_mov_b32 m0, s7
	v_lshl_add_u64 v[194:195], s[78:79], 0, v[134:135]
	global_load_lds_dwordx4 v[192:193], off
	s_mov_b32 m0, s8
	s_nop 0
	global_load_lds_dwordx4 v[194:195], off
	s_waitcnt vmcnt(8)
	s_waitcnt lgkmcnt(0)
	s_setprio 1
	v_mfma_f32_16x16x32_bf16 v[68:71], v[148:151], v[184:187], v[68:71]
	v_mfma_f32_16x16x32_bf16 v[64:67], v[156:159], v[184:187], v[64:67]
	v_mfma_f32_16x16x32_bf16 v[84:87], v[148:151], v[222:225], v[84:87]
	v_mfma_f32_16x16x32_bf16 v[80:83], v[156:159], v[222:225], v[80:83]
	s_barrier
; #define PG8_STAGE(bufoff, gbase, voff) do { _Pragma("unroll") for (int _i = 0; _i < 2; ++_i) \
;         __builtin_amdgcn_global_load_lds((const unsigned*)((const char*)(gbase) + (voff)[_i]), (LAS unsigned*)(lds + (bufoff) + ldsw + _i * 8192), 16, 0, 0); } while (0)
; #define PG8_LDA(dst, b, h) do { _Pragma("unroll") for (int m = 0; m < 4; ++m) _Pragma("unroll") for (int k = 0; k < 2; ++k) dst[m][k] = *(const LAS bf16x8*)(lds + PG8_SA(b, h) + aoff + m * 2048 + k * 1024); } while (0)
; #define PG8_LDB(dst, b, h) do { _Pragma("unroll") for (int n = 0; n < 2; ++n) _Pragma("unroll") for (int k = 0; k < 2; ++k) dst[n][k] = *(const LAS bf16x8*)(lds + PG8_SB(b, h) + boff + n * 2048 + k * 1024); } while (0)
; #define PG8_MMA(ai, bj, At, Bt) do { __builtin_amdgcn_s_setprio(1); _Pragma("unroll") for (int m = 0; m < 4; ++m) _Pragma("unroll") for (int n = 0; n < 2; ++n) _Pragma("unroll") for (int k = 0; k < 2; ++k) \
;         acc[ai][bj][m][n] = __builtin_amdgcn_mfma_f32_16x16x32_bf16(Bt[n][k], At[m][k], acc[ai][bj][m][n], 0, 0, 0); __builtin_amdgcn_s_setprio(0); } while (0)
; #define PG8_WAIT_V(n) asm volatile("s_waitcnt vmcnt(" #n ")" ::: "memory")
; #define PG8_WAIT_L(n) asm volatile("s_waitcnt lgkmcnt(" #n ")" ::: "memory")
; #define PG8_BAR __builtin_amdgcn_s_barrier()
; #define PG8_SCHED __builtin_amdgcn_sched_barrier(0)
; template <class Epi, bool ALIGN_EPI, bool SP2, bool ROWHALF = false>
; DI void gemm_phase(LAS unsigned char* lds, const Gemm g, const StaticOrder& S, const Epi& E) {
;     ...
;             PG8_WAIT_V(8); PG8_WAIT_L(0); PG8_BAR; if constexpr (!ROWHALF) { PG8_MMA(1, 0, At, B0); PG8_MMA(1, 1, At, B1); } PG8_BAR; PG8_SCHED;
;             PG8_LDB(B0, 1, 0); PG8_LDB(B1, 1, 1); PG8_SCHED; PG8_LDA(At, 1, 0); PG8_STAGE(PG8_SA(0, 1), a2 + hA1, voffA);
;             PG8_WAIT_V(8); PG8_WAIT_L(0); PG8_BAR; PG8_MMA(0, 0, At, B0); PG8_MMA(0, 1, At, B1); PG8_BAR; PG8_SCHED;
	v_mfma_f32_16x16x32_bf16 v[114:117], v[148:151], v[230:233], v[114:117]
	v_mfma_f32_16x16x32_bf16 v[104:107], v[156:159], v[230:233], v[104:107]
	v_mfma_f32_16x16x32_bf16 v[118:121], v[148:151], v[238:241], v[118:121]
	v_mfma_f32_16x16x32_bf16 v[110:113], v[156:159], v[238:241], v[110:113]
	v_mfma_f32_16x16x32_bf16 v[68:71], v[152:155], v[218:221], v[68:71]
	v_mfma_f32_16x16x32_bf16 v[64:67], v[164:167], v[218:221], v[64:67]
	v_mfma_f32_16x16x32_bf16 v[84:87], v[152:155], v[226:229], v[84:87]
	v_mfma_f32_16x16x32_bf16 v[80:83], v[164:167], v[226:229], v[80:83]
	v_mfma_f32_16x16x32_bf16 v[114:117], v[152:155], v[234:237], v[114:117]
	v_mfma_f32_16x16x32_bf16 v[104:107], v[164:167], v[234:237], v[104:107]
	v_mfma_f32_16x16x32_bf16 v[118:121], v[152:155], v[242:245], v[118:121]
	v_mfma_f32_16x16x32_bf16 v[110:113], v[164:167], v[242:245], v[110:113]
	s_setprio 0
	s_setprio 1
	v_mfma_f32_16x16x32_bf16 v[76:79], v[168:171], v[184:187], v[76:79]
	v_mfma_f32_16x16x32_bf16 v[72:75], v[176:179], v[184:187], v[72:75]
	v_mfma_f32_16x16x32_bf16 v[92:95], v[168:171], v[222:225], v[92:95]
	v_mfma_f32_16x16x32_bf16 v[88:91], v[176:179], v[222:225], v[88:91]
	v_mfma_f32_16x16x32_bf16 v[126:129], v[168:171], v[230:233], v[126:129]
	v_mfma_f32_16x16x32_bf16 v[122:125], v[176:179], v[230:233], v[122:125]
	v_mfma_f32_16x16x32_bf16 v[98:101], v[168:171], v[238:241], v[100:103]
	v_mfma_f32_16x16x32_bf16 v[130:133], v[176:179], v[238:241], v[130:133]
	v_mfma_f32_16x16x32_bf16 v[76:79], v[172:175], v[218:221], v[76:79]
	v_mfma_f32_16x16x32_bf16 v[72:75], v[180:183], v[218:221], v[72:75]
	v_mfma_f32_16x16x32_bf16 v[92:95], v[172:175], v[226:229], v[92:95]
	v_mfma_f32_16x16x32_bf16 v[88:91], v[180:183], v[226:229], v[88:91]
	v_mfma_f32_16x16x32_bf16 v[126:129], v[172:175], v[234:237], v[126:129]
	v_mfma_f32_16x16x32_bf16 v[122:125], v[180:183], v[234:237], v[122:125]
	v_mfma_f32_16x16x32_bf16 v[98:101], v[172:175], v[242:245], v[98:101]
	v_mfma_f32_16x16x32_bf16 v[130:133], v[180:183], v[242:245], v[130:133]
	s_setprio 0
	s_barrier
	s_add_i32 s37, 0, 0x18000
	v_add_u32_e32 v96, s37, v146
	s_add_i32 s81, 0, 0x1c000
	ds_read_b128 v[148:151], v96
	ds_read_b128 v[152:155], v96 offset:1024
	ds_read_b128 v[156:159], v96 offset:2048
	ds_read_b128 v[164:167], v96 offset:3072
	v_add_u32_e32 v96, s81, v146
	ds_read_b128 v[168:171], v96
	ds_read_b128 v[172:175], v96 offset:1024
	ds_read_b128 v[176:179], v96 offset:2048
	ds_read_b128 v[180:183], v96 offset:3072
	s_add_u32 s78, s78, s18
	s_addc_u32 s79, s79, 0
	s_mov_b32 m0, s9
	v_lshl_add_u64 v[102:103], s[78:79], 0, v[138:139]
	ds_read_b128 v[184:187], v147 offset:32768
	ds_read_b128 v[218:221], v147 offset:33792
	ds_read_b128 v[222:225], v147 offset:34816
	ds_read_b128 v[226:229], v147 offset:35840
	ds_read_b128 v[230:233], v147 offset:36864
	ds_read_b128 v[234:237], v147 offset:37888
	ds_read_b128 v[238:241], v147 offset:38912
	ds_read_b128 v[242:245], v147 offset:39936
	global_load_lds_dwordx4 v[102:103], off
	v_lshl_add_u64 v[102:103], s[78:79], 0, v[134:135]
	s_mov_b32 m0, s10
	s_nop 0
	global_load_lds_dwordx4 v[102:103], off
	s_waitcnt vmcnt(8)
	s_waitcnt lgkmcnt(0)
	s_setprio 1
	v_mfma_f32_16x16x32_bf16 v[4:7], v[148:151], v[184:187], v[4:7]
	v_mfma_f32_16x16x32_bf16 v[0:3], v[156:159], v[184:187], v[0:3]
	v_mfma_f32_16x16x32_bf16 v[20:23], v[148:151], v[222:225], v[20:23]
	v_mfma_f32_16x16x32_bf16 v[16:19], v[156:159], v[222:225], v[16:19]
	s_barrier
	v_mfma_f32_16x16x32_bf16 v[36:39], v[148:151], v[230:233], v[36:39]
	v_mfma_f32_16x16x32_bf16 v[32:35], v[156:159], v[230:233], v[32:35]
	v_mfma_f32_16x16x32_bf16 v[52:55], v[148:151], v[238:241], v[52:55]
	v_mfma_f32_16x16x32_bf16 v[48:51], v[156:159], v[238:241], v[48:51]
	v_mfma_f32_16x16x32_bf16 v[4:7], v[152:155], v[218:221], v[4:7]
	v_mfma_f32_16x16x32_bf16 v[0:3], v[164:167], v[218:221], v[0:3]
	v_mfma_f32_16x16x32_bf16 v[20:23], v[152:155], v[226:229], v[20:23]
	v_mfma_f32_16x16x32_bf16 v[16:19], v[164:167], v[226:229], v[16:19]
	v_mfma_f32_16x16x32_bf16 v[36:39], v[152:155], v[234:237], v[36:39]
	v_mfma_f32_16x16x32_bf16 v[32:35], v[164:167], v[234:237], v[32:35]
	v_mfma_f32_16x16x32_bf16 v[52:55], v[152:155], v[242:245], v[52:55]
	v_mfma_f32_16x16x32_bf16 v[48:51], v[164:167], v[242:245], v[48:51]
	s_setprio 0
	s_setprio 1
	v_mfma_f32_16x16x32_bf16 v[12:15], v[168:171], v[184:187], v[12:15]
	v_mfma_f32_16x16x32_bf16 v[8:11], v[176:179], v[184:187], v[8:11]
	v_mfma_f32_16x16x32_bf16 v[28:31], v[168:171], v[222:225], v[28:31]
	v_mfma_f32_16x16x32_bf16 v[24:27], v[176:179], v[222:225], v[24:27]
	v_mfma_f32_16x16x32_bf16 v[44:47], v[168:171], v[230:233], v[44:47]
	v_mfma_f32_16x16x32_bf16 v[40:43], v[176:179], v[230:233], v[40:43]
	v_mfma_f32_16x16x32_bf16 v[60:63], v[168:171], v[238:241], v[60:63]
	v_mfma_f32_16x16x32_bf16 v[56:59], v[176:179], v[238:241], v[56:59]
	v_mfma_f32_16x16x32_bf16 v[12:15], v[172:175], v[218:221], v[12:15]
	v_mfma_f32_16x16x32_bf16 v[8:11], v[180:183], v[218:221], v[8:11]
	v_mfma_f32_16x16x32_bf16 v[28:31], v[172:175], v[226:229], v[28:31]
	v_mfma_f32_16x16x32_bf16 v[24:27], v[180:183], v[226:229], v[24:27]
	v_mfma_f32_16x16x32_bf16 v[44:47], v[172:175], v[234:237], v[44:47]
	v_mfma_f32_16x16x32_bf16 v[40:43], v[180:183], v[234:237], v[40:43]
	v_mfma_f32_16x16x32_bf16 v[60:63], v[172:175], v[242:245], v[60:63]
	v_mfma_f32_16x16x32_bf16 v[56:59], v[180:183], v[242:245], v[56:59]
	s_setprio 0
	s_barrier
; #define PG8_STAGE(bufoff, gbase, voff) do { _Pragma("unroll") for (int _i = 0; _i < 2; ++_i) \
;         __builtin_amdgcn_global_load_lds((const unsigned*)((const char*)(gbase) + (voff)[_i]), (LAS unsigned*)(lds + (bufoff) + ldsw + _i * 8192), 16, 0, 0); } while (0)
; #define PG8_LDA(dst, b, h) do { _Pragma("unroll") for (int m = 0; m < 4; ++m) _Pragma("unroll") for (int k = 0; k < 2; ++k) dst[m][k] = *(const LAS bf16x8*)(lds + PG8_SA(b, h) + aoff + m * 2048 + k * 1024); } while (0)
; #define PG8_MMA(ai, bj, At, Bt) do { __builtin_amdgcn_s_setprio(1); _Pragma("unroll") for (int m = 0; m < 4; ++m) _Pragma("unroll") for (int n = 0; n < 2; ++n) _Pragma("unroll") for (int k = 0; k < 2; ++k) \
;         acc[ai][bj][m][n] = __builtin_amdgcn_mfma_f32_16x16x32_bf16(Bt[n][k], At[m][k], acc[ai][bj][m][n], 0, 0, 0); __builtin_amdgcn_s_setprio(0); } while (0)
; #define PG8_WAIT_V(n) asm volatile("s_waitcnt vmcnt(" #n ")" ::: "memory")
; #define PG8_WAIT_L(n) asm volatile("s_waitcnt lgkmcnt(" #n ")" ::: "memory")
; #define PG8_BAR __builtin_amdgcn_s_barrier()
; #define PG8_SCHED __builtin_amdgcn_sched_barrier(0)
; template <class Epi, bool ALIGN_EPI, bool SP2, bool ROWHALF = false>
; DI void gemm_phase(LAS unsigned char* lds, const Gemm g, const StaticOrder& S, const Epi& E) {
;     ...
;             if constexpr (!ROWHALF) { PG8_LDA(At, 1, 1); } PG8_STAGE(PG8_SB(1, 0), b3, voffB); PG8_STAGE(PG8_SB(1, 1), b3 + hstepB, voffB); PG8_STAGE(PG8_SA(1, 0), a3 + hA0, voffA);
;             PG8_WAIT_V(8); PG8_WAIT_L(0); PG8_BAR; if constexpr (!ROWHALF) { PG8_MMA(1, 0, At, B0); PG8_MMA(1, 1, At, B1); } PG8_BAR; PG8_SCHED;
;     ...
;         if (!has_next) break;
; #pragma unroll
;         for (int a = 0; a < 2; ++a)
; #pragma unroll
;             for (int b = 0; b < 2; ++b)
; #pragma unroll
;                 for (int m = 0; m < 4; ++m)
; #pragma unroll
;                     for (int n = 0; n < 2; ++n) acc[a][b][m][n] = (f32x4){0.f, 0.f, 0.f, 0.f};
;         cur = nxt; cA = nA; cB = nB; ++ui;
;         if constexpr (ALIGN_EPI) { if (wr == 1) PG8_BAR; }
;     }
	s_add_i32 s37, s37, s4
	v_lshl_add_u64 v[102:103], v[160:161], 0, s[38:39]
	s_mov_b32 m0, s37
	ds_read_b128 v[184:187], v147 offset:49152
	ds_read_b128 v[218:221], v147 offset:50176
	ds_read_b128 v[222:225], v147 offset:51200
	ds_read_b128 v[226:229], v147 offset:52224
	ds_read_b128 v[230:233], v147 offset:53248
	ds_read_b128 v[234:237], v147 offset:54272
	ds_read_b128 v[238:241], v147 offset:55296
	ds_read_b128 v[242:245], v147 offset:56320
	global_load_lds_dwordx4 v[102:103], off
	v_lshl_add_u64 v[102:103], v[246:247], 0, s[38:39]
	s_add_i32 m0, s37, 0x2000
	s_add_i32 s37, s81, s4
	global_load_lds_dwordx4 v[102:103], off
	v_lshl_add_u64 v[102:103], v[248:249], 0, s[38:39]
	s_mov_b32 m0, s37
	s_nop 0
	global_load_lds_dwordx4 v[102:103], off
	v_lshl_add_u64 v[102:103], v[250:251], 0, s[38:39]
	s_add_i32 m0, s37, 0x2000
	s_nop 0
	global_load_lds_dwordx4 v[102:103], off
	v_lshl_add_u64 v[102:103], v[192:193], 0, s[38:39]
	s_mov_b32 m0, s46
	s_nop 0
	global_load_lds_dwordx4 v[102:103], off
	v_lshl_add_u64 v[102:103], v[194:195], 0, s[38:39]
	s_mov_b32 m0, s47
	s_nop 0
	global_load_lds_dwordx4 v[102:103], off
	s_waitcnt vmcnt(8)
	s_waitcnt lgkmcnt(0)
	s_setprio 1
	v_mfma_f32_16x16x32_bf16 v[68:71], v[148:151], v[184:187], v[68:71]
	v_mfma_f32_16x16x32_bf16 v[64:67], v[156:159], v[184:187], v[64:67]
	v_mfma_f32_16x16x32_bf16 v[84:87], v[148:151], v[222:225], v[84:87]
	v_mfma_f32_16x16x32_bf16 v[80:83], v[156:159], v[222:225], v[80:83]
	s_barrier
	v_mfma_f32_16x16x32_bf16 v[114:117], v[148:151], v[230:233], v[114:117]
	v_mfma_f32_16x16x32_bf16 v[102:105], v[156:159], v[230:233], v[104:107]
	v_mfma_f32_16x16x32_bf16 v[118:121], v[148:151], v[238:241], v[118:121]
	v_mfma_f32_16x16x32_bf16 v[110:113], v[156:159], v[238:241], v[110:113]
	v_mfma_f32_16x16x32_bf16 v[68:71], v[152:155], v[218:221], v[68:71]
	v_mfma_f32_16x16x32_bf16 v[64:67], v[164:167], v[218:221], v[64:67]
	v_mfma_f32_16x16x32_bf16 v[84:87], v[152:155], v[226:229], v[84:87]
	v_mfma_f32_16x16x32_bf16 v[80:83], v[164:167], v[226:229], v[80:83]
	v_mfma_f32_16x16x32_bf16 v[114:117], v[152:155], v[234:237], v[114:117]
	v_mfma_f32_16x16x32_bf16 v[104:107], v[164:167], v[234:237], v[102:105]
	v_mfma_f32_16x16x32_bf16 v[118:121], v[152:155], v[242:245], v[118:121]
	v_mfma_f32_16x16x32_bf16 v[110:113], v[164:167], v[242:245], v[110:113]
	s_setprio 0
	s_setprio 1
	v_mfma_f32_16x16x32_bf16 v[76:79], v[168:171], v[184:187], v[76:79]
	v_mfma_f32_16x16x32_bf16 v[72:75], v[176:179], v[184:187], v[72:75]
	v_mfma_f32_16x16x32_bf16 v[92:95], v[168:171], v[222:225], v[92:95]
	v_mfma_f32_16x16x32_bf16 v[88:91], v[176:179], v[222:225], v[88:91]
	v_mfma_f32_16x16x32_bf16 v[126:129], v[168:171], v[230:233], v[126:129]
	v_mfma_f32_16x16x32_bf16 v[122:125], v[176:179], v[230:233], v[122:125]
	v_mfma_f32_16x16x32_bf16 v[98:101], v[168:171], v[238:241], v[98:101]
	v_mfma_f32_16x16x32_bf16 v[130:133], v[176:179], v[238:241], v[130:133]
	v_mfma_f32_16x16x32_bf16 v[76:79], v[172:175], v[218:221], v[76:79]
	v_mfma_f32_16x16x32_bf16 v[72:75], v[180:183], v[218:221], v[72:75]
	v_mfma_f32_16x16x32_bf16 v[92:95], v[172:175], v[226:229], v[92:95]
	v_mfma_f32_16x16x32_bf16 v[88:91], v[180:183], v[226:229], v[88:91]
	v_mfma_f32_16x16x32_bf16 v[126:129], v[172:175], v[234:237], v[126:129]
	v_mfma_f32_16x16x32_bf16 v[122:125], v[180:183], v[234:237], v[122:125]
	v_mfma_f32_16x16x32_bf16 v[100:103], v[172:175], v[242:245], v[98:101]
	v_mfma_f32_16x16x32_bf16 v[130:133], v[180:183], v[242:245], v[130:133]
	s_setprio 0
	s_barrier
	s_add_u32 s76, s76, 0x100
	s_addc_u32 s77, s77, 0
	s_add_u32 s20, s20, 0x100
	s_addc_u32 s21, s21, 0
	s_cmp_ge_u32 s36, s29
	s_mov_b32 s37, s36
	s_cbranch_scc0 .LBB0_159
	v_mov_b32_e32 v248, v217
	v_mov_b32_e32 v250, v207
	v_mov_b32_e32 v207, v196
	v_mov_b32_e32 v196, v197
	v_mov_b32_e32 v197, v198
	v_mov_b32_e32 v198, v199
	v_mov_b32_e32 v199, v200
	v_mov_b32_e32 v200, v201
	v_mov_b32_e32 v201, v202
	v_mov_b32_e32 v202, v203
	v_mov_b32_e32 v203, v204
	v_mov_b32_e32 v204, v205
	v_mov_b32_e32 v205, v206
	s_and_b64 vcc, exec, s[42:43]
	s_cbranch_vccnz .LBB0_152
	s_branch .LBB0_164

; #define PG8_STAGE(bufoff, gbase, voff) do { _Pragma("unroll") for (int _i = 0; _i < 2; ++_i) \
;         __builtin_amdgcn_global_load_lds((const unsigned*)((const char*)(gbase) + (voff)[_i]), (LAS unsigned*)(lds + (bufoff) + ldsw + _i * 8192), 16, 0, 0); } while (0)
; #define PG8_LDA(dst, b, h) do { _Pragma("unroll") for (int m = 0; m < 4; ++m) _Pragma("unroll") for (int k = 0; k < 2; ++k) dst[m][k] = *(const LAS bf16x8*)(lds + PG8_SA(b, h) + aoff + m * 2048 + k * 1024); } while (0)
; #define PG8_LDB(dst, b, h) do { _Pragma("unroll") for (int n = 0; n < 2; ++n) _Pragma("unroll") for (int k = 0; k < 2; ++k) dst[n][k] = *(const LAS bf16x8*)(lds + PG8_SB(b, h) + boff + n * 2048 + k * 1024); } while (0)
; #define PG8_MMA(ai, bj, At, Bt) do { __builtin_amdgcn_s_setprio(1); _Pragma("unroll") for (int m = 0; m < 4; ++m) _Pragma("unroll") for (int n = 0; n < 2; ++n) _Pragma("unroll") for (int k = 0; k < 2; ++k) \
;         acc[ai][bj][m][n] = __builtin_amdgcn_mfma_f32_16x16x32_bf16(Bt[n][k], At[m][k], acc[ai][bj][m][n], 0, 0, 0); __builtin_amdgcn_s_setprio(0); } while (0)
; #define PG8_WAIT_V(n) asm volatile("s_waitcnt vmcnt(" #n ")" ::: "memory")
; #define PG8_WAIT_L(n) asm volatile("s_waitcnt lgkmcnt(" #n ")" ::: "memory")
; template <class Epi, bool ALIGN_EPI, bool SP2, bool ROWHALF = false>
; DI void gemm_phase(LAS unsigned char* lds, const Gemm g, const StaticOrder& S, const Epi& E) {
;     ...
;         for (int t = 0; t < nt; t += 2) {
;             const bool last = (t == nt - 2);
;             const char* a1 = cA + (size_t)(t + 1) * kstep;
;             const char* a2 = last ? nA : cA + (size_t)(t + 2) * kstep; const char* b2 = last ? nB : cB + (size_t)(t + 2) * kstep;
;             const char* a3 = a2 + kstep; const char* b3 = b2 + kstep;
;             if constexpr (SP2) {
;             PG8_LDB(B0, 0, 0); PG8_LDB(B1, 0, 1); PG8_SCHED; PG8_LDA(At, 0, 0); PG8_STAGE(PG8_SA(1, 1), a1 + hA1, voffA);
;             PG8_WAIT_V(8); PG8_WAIT_L(0); PG8_BAR; PG8_MMA(0, 0, At, B0); PG8_MMA(0, 1, At, B1); PG8_BAR; PG8_SCHED;
;             if constexpr (!ROWHALF) { PG8_LDA(At, 0, 1); } PG8_STAGE(PG8_SB(0, 0), b2, voffB); PG8_STAGE(PG8_SB(0, 1), b2 + hstepB, voffB); PG8_STAGE(PG8_SA(0, 0), a2 + hA0, voffA);
;             PG8_WAIT_V(8); PG8_WAIT_L(0); PG8_BAR; if constexpr (!ROWHALF) { PG8_MMA(1, 0, At, B0); PG8_MMA(1, 1, At, B1); } PG8_BAR; PG8_SCHED;
.LBB0_240:
	s_add_u32 s36, s74, 0xfff80080
	s_addc_u32 s37, s75, -1
	s_add_i32 s54, 0, 0x10000
	s_cmp_eq_u32 s53, 28
	s_cselect_b32 s79, s20, s37
	s_cselect_b32 s78, s21, s36
	s_cselect_b32 s77, s29, s51
	s_cselect_b32 s76, s43, s47
	s_add_i32 s55, 0, 0x14000
	v_add_u32_e32 v156, s54, v145
	v_add_u32_e32 v160, s55, v145
	ds_read_b128 v[140:143], v156
	ds_read_b128 v[148:151], v156 offset:1024
	ds_read_b128 v[152:155], v156 offset:2048
	ds_read_b128 v[156:159], v156 offset:3072
	ds_read_b128 v[164:167], v160
	ds_read_b128 v[168:171], v160 offset:1024
	ds_read_b128 v[172:175], v160 offset:2048
	ds_read_b128 v[176:179], v160 offset:3072
	v_lshl_add_u64 v[160:161], s[74:75], 0, v[136:137]
	s_add_i32 m0, s9, 0xc000
	ds_read_b128 v[180:183], v147
	ds_read_b128 v[184:187], v147 offset:1024
	ds_read_b128 v[216:219], v147 offset:2048
	ds_read_b128 v[220:223], v147 offset:3072
	ds_read_b128 v[224:227], v147 offset:4096
	ds_read_b128 v[228:231], v147 offset:5120
	ds_read_b128 v[232:235], v147 offset:6144
	ds_read_b128 v[236:239], v147 offset:7168
	global_load_lds_dwordx4 v[160:161], off
	v_lshl_add_u64 v[160:161], s[74:75], 0, v[138:139]
	s_add_i32 m0, s9, 0xe000
	s_nop 0
	global_load_lds_dwordx4 v[160:161], off
	s_waitcnt vmcnt(8)
	s_waitcnt lgkmcnt(0)
	s_setprio 1
	v_mfma_f32_16x16x32_bf16 v[126:129], v[140:143], v[180:183], v[126:129]
	v_mfma_f32_16x16x32_bf16 v[118:121], v[152:155], v[180:183], v[118:121]
	v_mfma_f32_16x16x32_bf16 v[110:113], v[140:143], v[216:219], v[110:113]
	v_mfma_f32_16x16x32_bf16 v[102:105], v[152:155], v[216:219], v[102:105]
	s_barrier
	v_mfma_f32_16x16x32_bf16 v[92:95], v[140:143], v[224:227], v[92:95]
	v_mfma_f32_16x16x32_bf16 v[84:87], v[152:155], v[224:227], v[84:87]
	v_mfma_f32_16x16x32_bf16 v[76:79], v[140:143], v[232:235], v[76:79]
	v_mfma_f32_16x16x32_bf16 v[68:71], v[152:155], v[232:235], v[68:71]
	v_mfma_f32_16x16x32_bf16 v[126:129], v[148:151], v[184:187], v[126:129]
	v_mfma_f32_16x16x32_bf16 v[118:121], v[156:159], v[184:187], v[118:121]
	v_mfma_f32_16x16x32_bf16 v[110:113], v[148:151], v[220:223], v[110:113]
	v_mfma_f32_16x16x32_bf16 v[102:105], v[156:159], v[220:223], v[102:105]
	v_mfma_f32_16x16x32_bf16 v[92:95], v[148:151], v[228:231], v[92:95]
	v_mfma_f32_16x16x32_bf16 v[84:87], v[156:159], v[228:231], v[84:87]
	v_mfma_f32_16x16x32_bf16 v[76:79], v[148:151], v[236:239], v[76:79]
	v_mfma_f32_16x16x32_bf16 v[68:71], v[156:159], v[236:239], v[68:71]
	s_setprio 0
	s_setprio 1
	v_mfma_f32_16x16x32_bf16 v[122:125], v[164:167], v[180:183], v[122:125]
	v_mfma_f32_16x16x32_bf16 v[114:117], v[172:175], v[180:183], v[114:117]
	v_mfma_f32_16x16x32_bf16 v[106:109], v[164:167], v[216:219], v[106:109]
	v_mfma_f32_16x16x32_bf16 v[98:101], v[172:175], v[216:219], v[98:101]
	v_mfma_f32_16x16x32_bf16 v[88:91], v[164:167], v[224:227], v[88:91]
	v_mfma_f32_16x16x32_bf16 v[80:83], v[172:175], v[224:227], v[80:83]
	v_mfma_f32_16x16x32_bf16 v[72:75], v[164:167], v[232:235], v[72:75]
	v_mfma_f32_16x16x32_bf16 v[64:67], v[172:175], v[232:235], v[64:67]
	v_mfma_f32_16x16x32_bf16 v[122:125], v[168:171], v[184:187], v[122:125]
	v_mfma_f32_16x16x32_bf16 v[114:117], v[176:179], v[184:187], v[114:117]
	v_mfma_f32_16x16x32_bf16 v[106:109], v[168:171], v[220:223], v[106:109]
	v_mfma_f32_16x16x32_bf16 v[98:101], v[176:179], v[220:223], v[98:101]
	v_mfma_f32_16x16x32_bf16 v[88:91], v[168:171], v[228:231], v[88:91]
	v_mfma_f32_16x16x32_bf16 v[80:83], v[176:179], v[228:231], v[80:83]
	v_mfma_f32_16x16x32_bf16 v[72:75], v[168:171], v[236:239], v[72:75]
	v_mfma_f32_16x16x32_bf16 v[64:67], v[176:179], v[236:239], v[64:67]
	s_setprio 0
	s_barrier
	s_add_i32 s36, s54, s8
	v_lshl_add_u64 v[160:161], s[76:77], 0, v[96:97]
	s_mov_b32 m0, s36
	ds_read_b128 v[180:183], v147 offset:16384
	ds_read_b128 v[184:187], v147 offset:17408
	ds_read_b128 v[216:219], v147 offset:18432
	ds_read_b128 v[220:223], v147 offset:19456
	ds_read_b128 v[224:227], v147 offset:20480
	ds_read_b128 v[228:231], v147 offset:21504
	ds_read_b128 v[232:235], v147 offset:22528
	ds_read_b128 v[236:239], v147 offset:23552
	global_load_lds_dwordx4 v[160:161], off
	s_add_i32 m0, s36, 0x2000
	s_add_u32 s36, s76, 0x80000
	v_lshl_add_u64 v[240:241], s[76:77], 0, v[130:131]
	s_addc_u32 s37, s77, 0
	s_add_i32 s54, s55, s8
	global_load_lds_dwordx4 v[240:241], off
	v_lshl_add_u64 v[242:243], s[36:37], 0, v[96:97]
	s_mov_b32 m0, s54
	v_lshl_add_u64 v[244:245], s[78:79], 0, v[132:133]
	global_load_lds_dwordx4 v[242:243], off
	v_lshl_add_u64 v[242:243], s[36:37], 0, v[130:131]
	s_add_i32 m0, s54, 0x2000
	s_nop 0
	global_load_lds_dwordx4 v[242:243], off
	v_lshl_add_u64 v[242:243], s[78:79], 0, v[134:135]
	s_mov_b32 m0, s9
	s_nop 0
	global_load_lds_dwordx4 v[242:243], off
	s_mov_b32 m0, s10
	s_nop 0
	global_load_lds_dwordx4 v[244:245], off
	s_waitcnt vmcnt(8)
	s_waitcnt lgkmcnt(0)
	s_setprio 1
	v_mfma_f32_16x16x32_bf16 v[60:63], v[140:143], v[180:183], v[60:63]
	v_mfma_f32_16x16x32_bf16 v[52:55], v[152:155], v[180:183], v[52:55]
	v_mfma_f32_16x16x32_bf16 v[44:47], v[140:143], v[216:219], v[44:47]
	v_mfma_f32_16x16x32_bf16 v[36:39], v[152:155], v[216:219], v[36:39]
	s_barrier
; #define PG8_STAGE(bufoff, gbase, voff) do { _Pragma("unroll") for (int _i = 0; _i < 2; ++_i) \
;         __builtin_amdgcn_global_load_lds((const unsigned*)((const char*)(gbase) + (voff)[_i]), (LAS unsigned*)(lds + (bufoff) + ldsw + _i * 8192), 16, 0, 0); } while (0)
; #define PG8_LDA(dst, b, h) do { _Pragma("unroll") for (int m = 0; m < 4; ++m) _Pragma("unroll") for (int k = 0; k < 2; ++k) dst[m][k] = *(const LAS bf16x8*)(lds + PG8_SA(b, h) + aoff + m * 2048 + k * 1024); } while (0)
; #define PG8_LDB(dst, b, h) do { _Pragma("unroll") for (int n = 0; n < 2; ++n) _Pragma("unroll") for (int k = 0; k < 2; ++k) dst[n][k] = *(const LAS bf16x8*)(lds + PG8_SB(b, h) + boff + n * 2048 + k * 1024); } while (0)
; #define PG8_MMA(ai, bj, At, Bt) do { __builtin_amdgcn_s_setprio(1); _Pragma("unroll") for (int m = 0; m < 4; ++m) _Pragma("unroll") for (int n = 0; n < 2; ++n) _Pragma("unroll") for (int k = 0; k < 2; ++k) \
;         acc[ai][bj][m][n] = __builtin_amdgcn_mfma_f32_16x16x32_bf16(Bt[n][k], At[m][k], acc[ai][bj][m][n], 0, 0, 0); __builtin_amdgcn_s_setprio(0); } while (0)
; #define PG8_WAIT_V(n) asm volatile("s_waitcnt vmcnt(" #n ")" ::: "memory")
; #define PG8_WAIT_L(n) asm volatile("s_waitcnt lgkmcnt(" #n ")" ::: "memory")
; #define PG8_BAR __builtin_amdgcn_s_barrier()
; #define PG8_SCHED __builtin_amdgcn_sched_barrier(0)
; template <class Epi, bool ALIGN_EPI, bool SP2, bool ROWHALF = false>
; DI void gemm_phase(LAS unsigned char* lds, const Gemm g, const StaticOrder& S, const Epi& E) {
;     ...
;             PG8_WAIT_V(8); PG8_WAIT_L(0); PG8_BAR; if constexpr (!ROWHALF) { PG8_MMA(1, 0, At, B0); PG8_MMA(1, 1, At, B1); } PG8_BAR; PG8_SCHED;
;             PG8_LDB(B0, 1, 0); PG8_LDB(B1, 1, 1); PG8_SCHED; PG8_LDA(At, 1, 0); PG8_STAGE(PG8_SA(0, 1), a2 + hA1, voffA);
;             PG8_WAIT_V(8); PG8_WAIT_L(0); PG8_BAR; PG8_MMA(0, 0, At, B0); PG8_MMA(0, 1, At, B1); PG8_BAR; PG8_SCHED;
	v_mfma_f32_16x16x32_bf16 v[28:31], v[140:143], v[224:227], v[28:31]
	v_mfma_f32_16x16x32_bf16 v[20:23], v[152:155], v[224:227], v[20:23]
	v_mfma_f32_16x16x32_bf16 v[12:15], v[140:143], v[232:235], v[12:15]
	v_mfma_f32_16x16x32_bf16 v[4:7], v[152:155], v[232:235], v[4:7]
	v_mfma_f32_16x16x32_bf16 v[60:63], v[148:151], v[184:187], v[60:63]
	v_mfma_f32_16x16x32_bf16 v[52:55], v[156:159], v[184:187], v[52:55]
	v_mfma_f32_16x16x32_bf16 v[44:47], v[148:151], v[220:223], v[44:47]
	v_mfma_f32_16x16x32_bf16 v[36:39], v[156:159], v[220:223], v[36:39]
	v_mfma_f32_16x16x32_bf16 v[28:31], v[148:151], v[228:231], v[28:31]
	v_mfma_f32_16x16x32_bf16 v[20:23], v[156:159], v[228:231], v[20:23]
	v_mfma_f32_16x16x32_bf16 v[12:15], v[148:151], v[236:239], v[12:15]
	v_mfma_f32_16x16x32_bf16 v[4:7], v[156:159], v[236:239], v[4:7]
	s_setprio 0
	s_setprio 1
	v_mfma_f32_16x16x32_bf16 v[56:59], v[164:167], v[180:183], v[56:59]
	v_mfma_f32_16x16x32_bf16 v[48:51], v[172:175], v[180:183], v[48:51]
	v_mfma_f32_16x16x32_bf16 v[40:43], v[164:167], v[216:219], v[40:43]
	v_mfma_f32_16x16x32_bf16 v[32:35], v[172:175], v[216:219], v[32:35]
	v_mfma_f32_16x16x32_bf16 v[24:27], v[164:167], v[224:227], v[24:27]
	v_mfma_f32_16x16x32_bf16 v[16:19], v[172:175], v[224:227], v[16:19]
	v_mfma_f32_16x16x32_bf16 v[8:11], v[164:167], v[232:235], v[8:11]
	v_mfma_f32_16x16x32_bf16 v[0:3], v[172:175], v[232:235], v[0:3]
	v_mfma_f32_16x16x32_bf16 v[56:59], v[168:171], v[184:187], v[56:59]
	v_mfma_f32_16x16x32_bf16 v[48:51], v[176:179], v[184:187], v[48:51]
	v_mfma_f32_16x16x32_bf16 v[40:43], v[168:171], v[220:223], v[40:43]
	v_mfma_f32_16x16x32_bf16 v[32:35], v[176:179], v[220:223], v[32:35]
	v_mfma_f32_16x16x32_bf16 v[24:27], v[168:171], v[228:231], v[24:27]
	v_mfma_f32_16x16x32_bf16 v[16:19], v[176:179], v[228:231], v[16:19]
	v_mfma_f32_16x16x32_bf16 v[8:11], v[168:171], v[236:239], v[8:11]
	v_mfma_f32_16x16x32_bf16 v[0:3], v[176:179], v[236:239], v[0:3]
	s_setprio 0
	s_barrier
	s_add_i32 s54, 0, 0x18000
	s_add_i32 s55, 0, 0x1c000
	v_add_u32_e32 v156, s54, v145
	v_add_u32_e32 v176, s55, v145
	ds_read_b128 v[140:143], v156
	ds_read_b128 v[148:151], v156 offset:1024
	ds_read_b128 v[152:155], v156 offset:2048
	ds_read_b128 v[156:159], v156 offset:3072
	ds_read_b128 v[164:167], v176
	ds_read_b128 v[168:171], v176 offset:1024
	ds_read_b128 v[172:175], v176 offset:2048
	ds_read_b128 v[176:179], v176 offset:3072
	s_add_u32 s36, s78, 0x80000
	s_addc_u32 s37, s79, 0
	s_mov_b32 m0, s11
	v_lshl_add_u64 v[246:247], s[36:37], 0, v[134:135]
	ds_read_b128 v[180:183], v147 offset:32768
	ds_read_b128 v[184:187], v147 offset:33792
	ds_read_b128 v[216:219], v147 offset:34816
	ds_read_b128 v[220:223], v147 offset:35840
	ds_read_b128 v[224:227], v147 offset:36864
	ds_read_b128 v[228:231], v147 offset:37888
	ds_read_b128 v[232:235], v147 offset:38912
	ds_read_b128 v[236:239], v147 offset:39936
	global_load_lds_dwordx4 v[246:247], off
	v_lshl_add_u64 v[246:247], s[36:37], 0, v[132:133]
	s_mov_b32 m0, s12
	s_nop 0
	global_load_lds_dwordx4 v[246:247], off
	s_waitcnt vmcnt(8)
	s_waitcnt lgkmcnt(0)
	s_setprio 1
	v_mfma_f32_16x16x32_bf16 v[126:129], v[140:143], v[180:183], v[126:129]
	v_mfma_f32_16x16x32_bf16 v[118:121], v[152:155], v[180:183], v[118:121]
	v_mfma_f32_16x16x32_bf16 v[110:113], v[140:143], v[216:219], v[110:113]
	v_mfma_f32_16x16x32_bf16 v[102:105], v[152:155], v[216:219], v[102:105]
	s_barrier
	v_mfma_f32_16x16x32_bf16 v[92:95], v[140:143], v[224:227], v[92:95]
	v_mfma_f32_16x16x32_bf16 v[84:87], v[152:155], v[224:227], v[84:87]
	v_mfma_f32_16x16x32_bf16 v[76:79], v[140:143], v[232:235], v[76:79]
	v_mfma_f32_16x16x32_bf16 v[68:71], v[152:155], v[232:235], v[68:71]
	v_mfma_f32_16x16x32_bf16 v[126:129], v[148:151], v[184:187], v[126:129]
	v_mfma_f32_16x16x32_bf16 v[118:121], v[156:159], v[184:187], v[118:121]
	v_mfma_f32_16x16x32_bf16 v[110:113], v[148:151], v[220:223], v[110:113]
	v_mfma_f32_16x16x32_bf16 v[102:105], v[156:159], v[220:223], v[102:105]
	v_mfma_f32_16x16x32_bf16 v[92:95], v[148:151], v[228:231], v[92:95]
	v_mfma_f32_16x16x32_bf16 v[84:87], v[156:159], v[228:231], v[84:87]
	v_mfma_f32_16x16x32_bf16 v[76:79], v[148:151], v[236:239], v[76:79]
	v_mfma_f32_16x16x32_bf16 v[68:71], v[156:159], v[236:239], v[68:71]
	s_setprio 0
	s_setprio 1
	v_mfma_f32_16x16x32_bf16 v[122:125], v[164:167], v[180:183], v[122:125]
	v_mfma_f32_16x16x32_bf16 v[114:117], v[172:175], v[180:183], v[114:117]
	v_mfma_f32_16x16x32_bf16 v[106:109], v[164:167], v[216:219], v[106:109]
	v_mfma_f32_16x16x32_bf16 v[98:101], v[172:175], v[216:219], v[98:101]
	v_mfma_f32_16x16x32_bf16 v[88:91], v[164:167], v[224:227], v[88:91]
	v_mfma_f32_16x16x32_bf16 v[80:83], v[172:175], v[224:227], v[80:83]
	v_mfma_f32_16x16x32_bf16 v[72:75], v[164:167], v[232:235], v[72:75]
	v_mfma_f32_16x16x32_bf16 v[64:67], v[172:175], v[232:235], v[64:67]
	v_mfma_f32_16x16x32_bf16 v[122:125], v[168:171], v[184:187], v[122:125]
	v_mfma_f32_16x16x32_bf16 v[114:117], v[176:179], v[184:187], v[114:117]
	v_mfma_f32_16x16x32_bf16 v[106:109], v[168:171], v[220:223], v[106:109]
	v_mfma_f32_16x16x32_bf16 v[98:101], v[176:179], v[220:223], v[98:101]
	v_mfma_f32_16x16x32_bf16 v[88:91], v[168:171], v[228:231], v[88:91]
	v_mfma_f32_16x16x32_bf16 v[80:83], v[176:179], v[228:231], v[80:83]
	v_mfma_f32_16x16x32_bf16 v[72:75], v[168:171], v[236:239], v[72:75]
	v_mfma_f32_16x16x32_bf16 v[64:67], v[176:179], v[236:239], v[64:67]
	s_setprio 0
	s_barrier
; #define PG8_STAGE(bufoff, gbase, voff) do { _Pragma("unroll") for (int _i = 0; _i < 2; ++_i) \
;         __builtin_amdgcn_global_load_lds((const unsigned*)((const char*)(gbase) + (voff)[_i]), (LAS unsigned*)(lds + (bufoff) + ldsw + _i * 8192), 16, 0, 0); } while (0)
; #define PG8_LDA(dst, b, h) do { _Pragma("unroll") for (int m = 0; m < 4; ++m) _Pragma("unroll") for (int k = 0; k < 2; ++k) dst[m][k] = *(const LAS bf16x8*)(lds + PG8_SA(b, h) + aoff + m * 2048 + k * 1024); } while (0)
; #define PG8_MMA(ai, bj, At, Bt) do { __builtin_amdgcn_s_setprio(1); _Pragma("unroll") for (int m = 0; m < 4; ++m) _Pragma("unroll") for (int n = 0; n < 2; ++n) _Pragma("unroll") for (int k = 0; k < 2; ++k) \
;         acc[ai][bj][m][n] = __builtin_amdgcn_mfma_f32_16x16x32_bf16(Bt[n][k], At[m][k], acc[ai][bj][m][n], 0, 0, 0); __builtin_amdgcn_s_setprio(0); } while (0)
; #define PG8_WAIT_V(n) asm volatile("s_waitcnt vmcnt(" #n ")" ::: "memory")
; #define PG8_WAIT_L(n) asm volatile("s_waitcnt lgkmcnt(" #n ")" ::: "memory")
; #define PG8_BAR __builtin_amdgcn_s_barrier()
; #define PG8_SCHED __builtin_amdgcn_sched_barrier(0)
; template <class Epi, bool ALIGN_EPI, bool SP2, bool ROWHALF = false>
; DI void gemm_phase(LAS unsigned char* lds, const Gemm g, const StaticOrder& S, const Epi& E) {
;     ...
;             if constexpr (!ROWHALF) { PG8_LDA(At, 1, 1); } PG8_STAGE(PG8_SB(1, 0), b3, voffB); PG8_STAGE(PG8_SB(1, 1), b3 + hstepB, voffB); PG8_STAGE(PG8_SA(1, 0), a3 + hA0, voffA);
;             PG8_WAIT_V(8); PG8_WAIT_L(0); PG8_BAR; if constexpr (!ROWHALF) { PG8_MMA(1, 0, At, B0); PG8_MMA(1, 1, At, B1); } PG8_BAR; PG8_SCHED;
;     ...
;         if constexpr (ALIGN_EPI) { if (wr == 0) PG8_BAR; }
	s_add_i32 s36, s54, s8
	v_lshl_add_u64 v[160:161], v[160:161], 0, s[38:39]
	s_mov_b32 m0, s36
	ds_read_b128 v[180:183], v147 offset:49152
	ds_read_b128 v[184:187], v147 offset:50176
	ds_read_b128 v[216:219], v147 offset:51200
	ds_read_b128 v[220:223], v147 offset:52224
	ds_read_b128 v[224:227], v147 offset:53248
	ds_read_b128 v[228:231], v147 offset:54272
	ds_read_b128 v[232:235], v147 offset:55296
	ds_read_b128 v[236:239], v147 offset:56320
	global_load_lds_dwordx4 v[160:161], off
	s_add_i32 m0, s36, 0x2000
	s_add_u32 s36, s76, 0x80080
	v_lshl_add_u64 v[160:161], v[240:241], 0, s[38:39]
	s_addc_u32 s37, s77, 0
	s_add_i32 s54, s55, s8
	global_load_lds_dwordx4 v[160:161], off
	v_lshl_add_u64 v[160:161], s[36:37], 0, v[96:97]
	s_mov_b32 m0, s54
	s_nop 0
	global_load_lds_dwordx4 v[160:161], off
	v_lshl_add_u64 v[160:161], s[36:37], 0, v[130:131]
	s_add_i32 m0, s54, 0x2000
	s_nop 0
	global_load_lds_dwordx4 v[160:161], off
	v_lshl_add_u64 v[160:161], v[242:243], 0, s[38:39]
	s_mov_b32 m0, s31
	s_nop 0
	global_load_lds_dwordx4 v[160:161], off
	v_lshl_add_u64 v[160:161], v[244:245], 0, s[38:39]
	s_mov_b32 m0, s46
	s_nop 0
	global_load_lds_dwordx4 v[160:161], off
	s_waitcnt vmcnt(8)
	s_waitcnt lgkmcnt(0)
	s_setprio 1
	v_mfma_f32_16x16x32_bf16 v[60:63], v[140:143], v[180:183], v[60:63]
	v_mfma_f32_16x16x32_bf16 v[52:55], v[152:155], v[180:183], v[52:55]
	v_mfma_f32_16x16x32_bf16 v[44:47], v[140:143], v[216:219], v[44:47]
	v_mfma_f32_16x16x32_bf16 v[36:39], v[152:155], v[216:219], v[36:39]
	s_barrier
	v_mfma_f32_16x16x32_bf16 v[28:31], v[140:143], v[224:227], v[28:31]
	v_mfma_f32_16x16x32_bf16 v[20:23], v[152:155], v[224:227], v[20:23]
	v_mfma_f32_16x16x32_bf16 v[12:15], v[140:143], v[232:235], v[12:15]
	v_mfma_f32_16x16x32_bf16 v[4:7], v[152:155], v[232:235], v[4:7]
	v_mfma_f32_16x16x32_bf16 v[60:63], v[148:151], v[184:187], v[60:63]
	v_mfma_f32_16x16x32_bf16 v[52:55], v[156:159], v[184:187], v[52:55]
	v_mfma_f32_16x16x32_bf16 v[44:47], v[148:151], v[220:223], v[44:47]
	v_mfma_f32_16x16x32_bf16 v[36:39], v[156:159], v[220:223], v[36:39]
	v_mfma_f32_16x16x32_bf16 v[28:31], v[148:151], v[228:231], v[28:31]
	v_mfma_f32_16x16x32_bf16 v[20:23], v[156:159], v[228:231], v[20:23]
	v_mfma_f32_16x16x32_bf16 v[12:15], v[148:151], v[236:239], v[12:15]
	v_mfma_f32_16x16x32_bf16 v[4:7], v[156:159], v[236:239], v[4:7]
	s_setprio 0
	s_setprio 1
	v_mfma_f32_16x16x32_bf16 v[56:59], v[164:167], v[180:183], v[56:59]
	v_mfma_f32_16x16x32_bf16 v[48:51], v[172:175], v[180:183], v[48:51]
	v_mfma_f32_16x16x32_bf16 v[40:43], v[164:167], v[216:219], v[40:43]
	v_mfma_f32_16x16x32_bf16 v[32:35], v[172:175], v[216:219], v[32:35]
	v_mfma_f32_16x16x32_bf16 v[24:27], v[164:167], v[224:227], v[24:27]
	v_mfma_f32_16x16x32_bf16 v[16:19], v[172:175], v[224:227], v[16:19]
	v_mfma_f32_16x16x32_bf16 v[8:11], v[164:167], v[232:235], v[8:11]
	v_mfma_f32_16x16x32_bf16 v[0:3], v[172:175], v[232:235], v[0:3]
	v_mfma_f32_16x16x32_bf16 v[56:59], v[168:171], v[184:187], v[56:59]
	v_mfma_f32_16x16x32_bf16 v[48:51], v[176:179], v[184:187], v[48:51]
	v_mfma_f32_16x16x32_bf16 v[40:43], v[168:171], v[220:223], v[40:43]
	v_mfma_f32_16x16x32_bf16 v[32:35], v[176:179], v[220:223], v[32:35]
	v_mfma_f32_16x16x32_bf16 v[24:27], v[168:171], v[228:231], v[24:27]
	v_mfma_f32_16x16x32_bf16 v[16:19], v[176:179], v[228:231], v[16:19]
	v_mfma_f32_16x16x32_bf16 v[8:11], v[168:171], v[236:239], v[8:11]
	v_mfma_f32_16x16x32_bf16 v[0:3], v[176:179], v[236:239], v[0:3]
	s_setprio 0
	s_barrier
	s_add_i32 s53, s53, 2
	s_add_u32 s74, s74, 0x100
	s_addc_u32 s75, s75, 0
	s_add_u32 s47, s47, 0x100
	s_addc_u32 s51, s51, 0
	s_cmp_gt_u32 s53, 29
	s_cbranch_scc0 .LBB0_240
	s_and_b64 vcc, exec, s[24:25]
	s_cbranch_vccz .LBB0_243
	s_barrier

; #define PG8_STAGE(bufoff, gbase, voff) do { _Pragma("unroll") for (int _i = 0; _i < 2; ++_i) \
;         __builtin_amdgcn_global_load_lds((const unsigned*)((const char*)(gbase) + (voff)[_i]), (LAS unsigned*)(lds + (bufoff) + ldsw + _i * 8192), 16, 0, 0); } while (0)
; #define PG8_LDA(dst, b, h) do { _Pragma("unroll") for (int m = 0; m < 4; ++m) _Pragma("unroll") for (int k = 0; k < 2; ++k) dst[m][k] = *(const LAS bf16x8*)(lds + PG8_SA(b, h) + aoff + m * 2048 + k * 1024); } while (0)
; #define PG8_LDB(dst, b, h) do { _Pragma("unroll") for (int n = 0; n < 2; ++n) _Pragma("unroll") for (int k = 0; k < 2; ++k) dst[n][k] = *(const LAS bf16x8*)(lds + PG8_SB(b, h) + boff + n * 2048 + k * 1024); } while (0)
; #define PG8_MMA(ai, bj, At, Bt) do { __builtin_amdgcn_s_setprio(1); _Pragma("unroll") for (int m = 0; m < 4; ++m) _Pragma("unroll") for (int n = 0; n < 2; ++n) _Pragma("unroll") for (int k = 0; k < 2; ++k) \
;         acc[ai][bj][m][n] = __builtin_amdgcn_mfma_f32_16x16x32_bf16(Bt[n][k], At[m][k], acc[ai][bj][m][n], 0, 0, 0); __builtin_amdgcn_s_setprio(0); } while (0)
; #define PG8_WAIT_V(n) asm volatile("s_waitcnt vmcnt(" #n ")" ::: "memory")
; #define PG8_WAIT_L(n) asm volatile("s_waitcnt lgkmcnt(" #n ")" ::: "memory")
; #define PG8_BAR __builtin_amdgcn_s_barrier()
; #define PG8_SCHED __builtin_amdgcn_sched_barrier(0)
; template <class Epi, bool ALIGN_EPI, bool SP2, bool ROWHALF = false>
; DI void gemm_phase(LAS unsigned char* lds, const Gemm g, const StaticOrder& S, const Epi& E) {
;     ...
;             PG8_LDB(B0, 0, 0); PG8_LDB(B1, 0, 1); PG8_SCHED; PG8_LDA(At, 0, 0); PG8_STAGE(PG8_SA(1, 1), a1 + hA1, voffA);
;             PG8_WAIT_V(8); PG8_WAIT_L(0); PG8_BAR; PG8_MMA(0, 0, At, B0); PG8_MMA(0, 1, At, B1); PG8_BAR; PG8_SCHED;
;             if constexpr (!ROWHALF) { PG8_LDA(At, 0, 1); } PG8_STAGE(PG8_SB(0, 0), b2, voffB); PG8_STAGE(PG8_SB(0, 1), b2 + hstepB, voffB); PG8_STAGE(PG8_SA(0, 0), a2 + hA0, voffA);
;             PG8_WAIT_V(8); PG8_WAIT_L(0); PG8_BAR; if constexpr (!ROWHALF) { PG8_MMA(1, 0, At, B0); PG8_MMA(1, 1, At, B1); } PG8_BAR; PG8_SCHED;
.LBB0_251:
	s_add_u32 s22, s28, s18
	s_addc_u32 s23, s29, s19
	s_add_u32 s22, s22, 0x18080100
	s_addc_u32 s23, s23, 0
	s_add_u32 s36, s4, s18
	s_addc_u32 s37, s5, s19
	s_add_i32 s40, 0, 0x10000
	s_cmpk_eq_i32 s18, 0xf00
	s_cselect_b32 s41, s13, s23
	s_cselect_b32 s42, s7, s22
	s_cselect_b32 s23, s17, s37
	s_cselect_b32 s22, s16, s36
	s_add_i32 s43, 0, 0x14000
	v_add_u32_e32 v90, s40, v76
	v_add_u32_e32 v94, s43, v76
	ds_read_b128 v[78:81], v90
	ds_read_b128 v[82:85], v90 offset:1024
	ds_read_b128 v[86:89], v90 offset:2048
	ds_read_b128 v[90:93], v90 offset:3072
	ds_read_b128 v[98:101], v94
	ds_read_b128 v[102:105], v94 offset:1024
	ds_read_b128 v[106:109], v94 offset:2048
	ds_read_b128 v[110:113], v94 offset:3072
	v_lshl_add_u64 v[94:95], v[72:73], 0, s[18:19]
	s_add_i32 m0, s6, 0xc000
	ds_read_b128 v[114:117], v77
	ds_read_b128 v[118:121], v77 offset:1024
	ds_read_b128 v[122:125], v77 offset:2048
	ds_read_b128 v[126:129], v77 offset:3072
	ds_read_b128 v[130:133], v77 offset:4096
	ds_read_b128 v[134:137], v77 offset:5120
	ds_read_b128 v[138:141], v77 offset:6144
	ds_read_b128 v[142:145], v77 offset:7168
	global_load_lds_dwordx4 v[94:95], off
	v_lshl_add_u64 v[94:95], v[70:71], 0, s[18:19]
	s_add_i32 m0, s6, 0xe000
	s_nop 0
	global_load_lds_dwordx4 v[94:95], off
	s_waitcnt vmcnt(8)
	s_waitcnt lgkmcnt(0)
	s_setprio 1
	v_mfma_f32_16x16x32_bf16 v[60:63], v[78:81], v[114:117], v[60:63]
	v_mfma_f32_16x16x32_bf16 v[52:55], v[86:89], v[114:117], v[52:55]
	v_mfma_f32_16x16x32_bf16 v[44:47], v[78:81], v[122:125], v[44:47]
	v_mfma_f32_16x16x32_bf16 v[36:39], v[86:89], v[122:125], v[36:39]
	s_barrier
	v_mfma_f32_16x16x32_bf16 v[28:31], v[78:81], v[130:133], v[28:31]
	v_mfma_f32_16x16x32_bf16 v[20:23], v[86:89], v[130:133], v[20:23]
	v_mfma_f32_16x16x32_bf16 v[12:15], v[78:81], v[138:141], v[12:15]
	v_mfma_f32_16x16x32_bf16 v[4:7], v[86:89], v[138:141], v[4:7]
	v_mfma_f32_16x16x32_bf16 v[60:63], v[82:85], v[118:121], v[60:63]
	v_mfma_f32_16x16x32_bf16 v[52:55], v[90:93], v[118:121], v[52:55]
	v_mfma_f32_16x16x32_bf16 v[44:47], v[82:85], v[126:129], v[44:47]
	v_mfma_f32_16x16x32_bf16 v[36:39], v[90:93], v[126:129], v[36:39]
	v_mfma_f32_16x16x32_bf16 v[28:31], v[82:85], v[134:137], v[28:31]
	v_mfma_f32_16x16x32_bf16 v[20:23], v[90:93], v[134:137], v[20:23]
	v_mfma_f32_16x16x32_bf16 v[12:15], v[82:85], v[142:145], v[12:15]
	v_mfma_f32_16x16x32_bf16 v[4:7], v[90:93], v[142:145], v[4:7]
	s_setprio 0
	s_setprio 1
	v_mfma_f32_16x16x32_bf16 v[56:59], v[98:101], v[114:117], v[56:59]
	v_mfma_f32_16x16x32_bf16 v[48:51], v[106:109], v[114:117], v[48:51]
	v_mfma_f32_16x16x32_bf16 v[40:43], v[98:101], v[122:125], v[40:43]
	v_mfma_f32_16x16x32_bf16 v[32:35], v[106:109], v[122:125], v[32:35]
	v_mfma_f32_16x16x32_bf16 v[24:27], v[98:101], v[130:133], v[24:27]
	v_mfma_f32_16x16x32_bf16 v[16:19], v[106:109], v[130:133], v[16:19]
	v_mfma_f32_16x16x32_bf16 v[8:11], v[98:101], v[138:141], v[8:11]
	v_mfma_f32_16x16x32_bf16 v[0:3], v[106:109], v[138:141], v[0:3]
	v_mfma_f32_16x16x32_bf16 v[56:59], v[102:105], v[118:121], v[56:59]
	v_mfma_f32_16x16x32_bf16 v[48:51], v[110:113], v[118:121], v[48:51]
	v_mfma_f32_16x16x32_bf16 v[40:43], v[102:105], v[126:129], v[40:43]
	v_mfma_f32_16x16x32_bf16 v[32:35], v[110:113], v[126:129], v[32:35]
	v_mfma_f32_16x16x32_bf16 v[24:27], v[102:105], v[134:137], v[24:27]
	v_mfma_f32_16x16x32_bf16 v[16:19], v[110:113], v[134:137], v[16:19]
	v_mfma_f32_16x16x32_bf16 v[8:11], v[102:105], v[142:145], v[8:11]
	v_mfma_f32_16x16x32_bf16 v[0:3], v[110:113], v[142:145], v[0:3]
	s_setprio 0
	s_barrier
	s_add_i32 s36, s40, s12
	v_lshl_add_u64 v[94:95], s[22:23], 0, v[96:97]
	s_mov_b32 m0, s36
	v_lshl_add_u64 v[146:147], s[22:23], 0, v[68:69]
	global_load_lds_dwordx4 v[94:95], off
	s_add_i32 m0, s36, 0x2000
	s_add_u32 s36, s22, 0x80000
	s_addc_u32 s37, s23, 0
	s_add_i32 s40, s43, s12
	global_load_lds_dwordx4 v[146:147], off
	v_lshl_add_u64 v[78:79], s[36:37], 0, v[96:97]
	s_mov_b32 m0, s40
	s_nop 0
	global_load_lds_dwordx4 v[78:79], off
	s_add_i32 m0, s40, 0x2000
	v_lshl_add_u64 v[78:79], s[36:37], 0, v[68:69]
	s_add_u32 s36, s42, s3
	s_addc_u32 s37, s41, 0
	global_load_lds_dwordx4 v[78:79], off
	v_lshl_add_u64 v[148:149], s[36:37], 0, v[64:65]
	s_mov_b32 m0, s6
	v_lshl_add_u64 v[150:151], s[36:37], 0, v[66:67]
	global_load_lds_dwordx4 v[148:149], off
	s_mov_b32 m0, s20
	s_nop 0
	global_load_lds_dwordx4 v[150:151], off
	s_waitcnt vmcnt(8)
	s_waitcnt lgkmcnt(0)
	s_barrier
; #define PG8_STAGE(bufoff, gbase, voff) do { _Pragma("unroll") for (int _i = 0; _i < 2; ++_i) \
;         __builtin_amdgcn_global_load_lds((const unsigned*)((const char*)(gbase) + (voff)[_i]), (LAS unsigned*)(lds + (bufoff) + ldsw + _i * 8192), 16, 0, 0); } while (0)
; #define PG8_LDA(dst, b, h) do { _Pragma("unroll") for (int m = 0; m < 4; ++m) _Pragma("unroll") for (int k = 0; k < 2; ++k) dst[m][k] = *(const LAS bf16x8*)(lds + PG8_SA(b, h) + aoff + m * 2048 + k * 1024); } while (0)
; #define PG8_LDB(dst, b, h) do { _Pragma("unroll") for (int n = 0; n < 2; ++n) _Pragma("unroll") for (int k = 0; k < 2; ++k) dst[n][k] = *(const LAS bf16x8*)(lds + PG8_SB(b, h) + boff + n * 2048 + k * 1024); } while (0)
; #define PG8_MMA(ai, bj, At, Bt) do { __builtin_amdgcn_s_setprio(1); _Pragma("unroll") for (int m = 0; m < 4; ++m) _Pragma("unroll") for (int n = 0; n < 2; ++n) _Pragma("unroll") for (int k = 0; k < 2; ++k) \
;         acc[ai][bj][m][n] = __builtin_amdgcn_mfma_f32_16x16x32_bf16(Bt[n][k], At[m][k], acc[ai][bj][m][n], 0, 0, 0); __builtin_amdgcn_s_setprio(0); } while (0)
; #define PG8_WAIT_V(n) asm volatile("s_waitcnt vmcnt(" #n ")" ::: "memory")
; #define PG8_WAIT_L(n) asm volatile("s_waitcnt lgkmcnt(" #n ")" ::: "memory")
; #define PG8_BAR __builtin_amdgcn_s_barrier()
; #define PG8_SCHED __builtin_amdgcn_sched_barrier(0)
; template <class Epi, bool ALIGN_EPI, bool SP2, bool ROWHALF = false>
; DI void gemm_phase(LAS unsigned char* lds, const Gemm g, const StaticOrder& S, const Epi& E) {
;     ...
;             PG8_WAIT_V(8); PG8_WAIT_L(0); PG8_BAR; if constexpr (!ROWHALF) { PG8_MMA(1, 0, At, B0); PG8_MMA(1, 1, At, B1); } PG8_BAR; PG8_SCHED;
;             PG8_LDB(B0, 1, 0); PG8_LDB(B1, 1, 1); PG8_SCHED; PG8_LDA(At, 1, 0); PG8_STAGE(PG8_SA(0, 1), a2 + hA1, voffA);
;             PG8_WAIT_V(8); PG8_WAIT_L(0); PG8_BAR; PG8_MMA(0, 0, At, B0); PG8_MMA(0, 1, At, B1); PG8_BAR; PG8_SCHED;
;             if constexpr (!ROWHALF) { PG8_LDA(At, 1, 1); } PG8_STAGE(PG8_SB(1, 0), b3, voffB); PG8_STAGE(PG8_SB(1, 1), b3 + hstepB, voffB); PG8_STAGE(PG8_SA(1, 0), a3 + hA0, voffA);
;             PG8_WAIT_V(8); PG8_WAIT_L(0); PG8_BAR; if constexpr (!ROWHALF) { PG8_MMA(1, 0, At, B0); PG8_MMA(1, 1, At, B1); } PG8_BAR; PG8_SCHED;
;     ...
;         if constexpr (ALIGN_EPI) { if (wr == 0) PG8_BAR; }
	s_barrier
	s_add_i32 s40, 0, 0x18000
	s_add_i32 s43, 0, 0x1c000
	v_add_u32_e32 v90, s40, v76
	v_add_u32_e32 v110, s43, v76
	ds_read_b128 v[78:81], v90
	ds_read_b128 v[82:85], v90 offset:1024
	ds_read_b128 v[86:89], v90 offset:2048
	ds_read_b128 v[90:93], v90 offset:3072
	ds_read_b128 v[98:101], v110
	ds_read_b128 v[102:105], v110 offset:1024
	ds_read_b128 v[106:109], v110 offset:2048
	ds_read_b128 v[110:113], v110 offset:3072
	s_add_u32 s36, s42, s8
	s_addc_u32 s37, s41, 0
	s_mov_b32 m0, s21
	v_lshl_add_u64 v[152:153], s[36:37], 0, v[64:65]
	ds_read_b128 v[114:117], v77 offset:32768
	ds_read_b128 v[118:121], v77 offset:33792
	ds_read_b128 v[122:125], v77 offset:34816
	ds_read_b128 v[126:129], v77 offset:35840
	ds_read_b128 v[130:133], v77 offset:36864
	ds_read_b128 v[134:137], v77 offset:37888
	ds_read_b128 v[138:141], v77 offset:38912
	ds_read_b128 v[142:145], v77 offset:39936
	global_load_lds_dwordx4 v[152:153], off
	v_lshl_add_u64 v[152:153], s[36:37], 0, v[66:67]
	s_mov_b32 m0, s24
	s_nop 0
	global_load_lds_dwordx4 v[152:153], off
	s_waitcnt vmcnt(8)
	s_waitcnt lgkmcnt(0)
	s_setprio 1
	v_mfma_f32_16x16x32_bf16 v[60:63], v[78:81], v[114:117], v[60:63]
	v_mfma_f32_16x16x32_bf16 v[52:55], v[86:89], v[114:117], v[52:55]
	v_mfma_f32_16x16x32_bf16 v[44:47], v[78:81], v[122:125], v[44:47]
	v_mfma_f32_16x16x32_bf16 v[36:39], v[86:89], v[122:125], v[36:39]
	s_barrier
	v_mfma_f32_16x16x32_bf16 v[28:31], v[78:81], v[130:133], v[28:31]
	v_mfma_f32_16x16x32_bf16 v[20:23], v[86:89], v[130:133], v[20:23]
	v_mfma_f32_16x16x32_bf16 v[12:15], v[78:81], v[138:141], v[12:15]
	v_mfma_f32_16x16x32_bf16 v[4:7], v[86:89], v[138:141], v[4:7]
	v_mfma_f32_16x16x32_bf16 v[60:63], v[82:85], v[118:121], v[60:63]
	v_mfma_f32_16x16x32_bf16 v[52:55], v[90:93], v[118:121], v[52:55]
	v_mfma_f32_16x16x32_bf16 v[44:47], v[82:85], v[126:129], v[44:47]
	v_mfma_f32_16x16x32_bf16 v[36:39], v[90:93], v[126:129], v[36:39]
	v_mfma_f32_16x16x32_bf16 v[28:31], v[82:85], v[134:137], v[28:31]
	v_mfma_f32_16x16x32_bf16 v[20:23], v[90:93], v[134:137], v[20:23]
	v_mfma_f32_16x16x32_bf16 v[12:15], v[82:85], v[142:145], v[12:15]
	v_mfma_f32_16x16x32_bf16 v[4:7], v[90:93], v[142:145], v[4:7]
	s_setprio 0
	s_setprio 1
	v_mfma_f32_16x16x32_bf16 v[56:59], v[98:101], v[114:117], v[56:59]
	v_mfma_f32_16x16x32_bf16 v[48:51], v[106:109], v[114:117], v[48:51]
	v_mfma_f32_16x16x32_bf16 v[40:43], v[98:101], v[122:125], v[40:43]
	v_mfma_f32_16x16x32_bf16 v[32:35], v[106:109], v[122:125], v[32:35]
	v_mfma_f32_16x16x32_bf16 v[24:27], v[98:101], v[130:133], v[24:27]
	v_mfma_f32_16x16x32_bf16 v[16:19], v[106:109], v[130:133], v[16:19]
	v_mfma_f32_16x16x32_bf16 v[8:11], v[98:101], v[138:141], v[8:11]
	v_mfma_f32_16x16x32_bf16 v[0:3], v[106:109], v[138:141], v[0:3]
	v_mfma_f32_16x16x32_bf16 v[56:59], v[102:105], v[118:121], v[56:59]
	v_mfma_f32_16x16x32_bf16 v[48:51], v[110:113], v[118:121], v[48:51]
	v_mfma_f32_16x16x32_bf16 v[40:43], v[102:105], v[126:129], v[40:43]
	v_mfma_f32_16x16x32_bf16 v[32:35], v[110:113], v[126:129], v[32:35]
	v_mfma_f32_16x16x32_bf16 v[24:27], v[102:105], v[134:137], v[24:27]
	v_mfma_f32_16x16x32_bf16 v[16:19], v[110:113], v[134:137], v[16:19]
	v_mfma_f32_16x16x32_bf16 v[8:11], v[102:105], v[142:145], v[8:11]
	v_mfma_f32_16x16x32_bf16 v[0:3], v[110:113], v[142:145], v[0:3]
	s_setprio 0
	s_barrier
	s_add_i32 s36, s40, s12
	v_lshl_add_u64 v[78:79], v[94:95], 0, s[38:39]
	s_mov_b32 m0, s36
	s_nop 0
	global_load_lds_dwordx4 v[78:79], off
	s_add_i32 m0, s36, 0x2000
	s_add_u32 s22, s22, 0x80080
	v_lshl_add_u64 v[78:79], v[146:147], 0, s[38:39]
	s_addc_u32 s23, s23, 0
	s_add_i32 s36, s43, s12
	global_load_lds_dwordx4 v[78:79], off
	v_lshl_add_u64 v[78:79], s[22:23], 0, v[96:97]
	s_mov_b32 m0, s36
	s_nop 0
	global_load_lds_dwordx4 v[78:79], off
	v_lshl_add_u64 v[78:79], s[22:23], 0, v[68:69]
	s_add_i32 m0, s36, 0x2000
	s_nop 0
	global_load_lds_dwordx4 v[78:79], off
	v_lshl_add_u64 v[78:79], v[148:149], 0, s[38:39]
	s_mov_b32 m0, s26
	s_nop 0
	global_load_lds_dwordx4 v[78:79], off
	v_lshl_add_u64 v[78:79], v[150:151], 0, s[38:39]
	s_mov_b32 m0, s27
	s_nop 0
	global_load_lds_dwordx4 v[78:79], off
	s_waitcnt vmcnt(8)
	s_waitcnt lgkmcnt(0)
	s_barrier
	s_barrier
	s_add_i32 s31, s31, 2
	s_add_u32 s18, s18, 0x100
	s_addc_u32 s19, s19, 0
	s_cmp_gt_u32 s31, 29
	s_cbranch_scc0 .LBB0_251
	s_cmpk_lt_u32 s9, 0x100
	s_cbranch_scc0 .LBB0_254
	s_barrier
